# stack1 + P6/P8 final K-loop iteration peeled: no dummy staging loads before the LayerNorm epilogue drain
# baseline (speedup 1.0000x reference)
; #define PG8_STAGE(bufoff, gbase, voff) do { _Pragma("unroll") for (int _i = 0; _i < 2; ++_i) \
;         __builtin_amdgcn_global_load_lds((const unsigned*)((const char*)(gbase) + (voff)[_i]), (PG8_LAS unsigned*)(lds + (bufoff) + ldsw + _i * 8192), 16, 0, 0); } while (0)
; #define PG8_LDA(dst, b, h) do { _Pragma("unroll") for (int m = 0; m < 4; ++m) _Pragma("unroll") for (int k = 0; k < 2; ++k) dst[m][k] = *(const PG8_LAS bf16x8*)(lds + PG8_SA(b, h) + aoff + m * 2048 + k * 1024); } while (0)
; #define PG8_LDB(dst, b, h) do { _Pragma("unroll") for (int n = 0; n < 2; ++n) _Pragma("unroll") for (int k = 0; k < 2; ++k) dst[n][k] = *(const PG8_LAS bf16x8*)(lds + PG8_SB(b, h) + boff + n * 2048 + k * 1024); } while (0)
; #define PG8_MMA(ai, bj, At, Bt) do { __builtin_amdgcn_s_setprio(1); _Pragma("unroll") for (int m = 0; m < 4; ++m) _Pragma("unroll") for (int n = 0; n < 2; ++n) _Pragma("unroll") for (int k = 0; k < 2; ++k) \
;         acc[ai][bj][m][n] = __builtin_amdgcn_mfma_f32_16x16x32_bf16(Bt[n][k], At[m][k], acc[ai][bj][m][n], 0, 0, 0); __builtin_amdgcn_s_setprio(0); } while (0)
; #define PG8_WAIT_V(n) asm volatile("s_waitcnt vmcnt(" #n ")" ::: "memory")
; #define PG8_BAR __builtin_amdgcn_s_barrier()
; template <class Epi, class Sched, bool ALIGN_EPI = false, bool SP2 = false>
; __device__ __forceinline__ void gemm_phase(PG8_LAS unsigned char* lds, const Gemm g, const Sched& S, const Epi& E) {
;     ...
;         for (int t = 0; t < nt; t += 2) {
;             const bool last = (t == nt - 2);
;             const char* a1 = cA + (size_t)(t + 1) * kstepA;
;             const char* a2 = last ? nA : cA + (size_t)(t + 2) * kstepA; const char* b2 = last ? nB : cB + (size_t)(t + 2) * kstep;
;             const char* a3 = a2 + kstepA; const char* b3 = b2 + kstep;
;             if (last && has_next) S.a_ready(nxt);
;             if constexpr (SP2) {
;             PG8_LDB(B0, 0, 0); PG8_LDB(B1, 0, 1); PG8_SCHED; PG8_LDA(At, 0, 0); PG8_STAGE(PG8_SA(1, 1), a1 + hstepA, voffA);
;             PG8_WAIT_V(8); PG8_WAIT_L(0); PG8_BAR; PG8_MMA(0, 0, At, B0); PG8_MMA(0, 1, At, B1); PG8_BAR; PG8_SCHED;
;             PG8_LDA(At, 0, 1); PG8_STAGE(PG8_SB(0, 0), b2, voffB); PG8_STAGE(PG8_SB(0, 1), b2 + hstepB, voffB); PG8_STAGE(PG8_SA(0, 0), a2, voffA);
;             PG8_WAIT_V(8); PG8_WAIT_L(0); PG8_BAR; PG8_MMA(1, 0, At, B0); PG8_MMA(1, 1, At, B1); PG8_BAR; PG8_SCHED;
.LBB0_1088:
	v_add_u32_e32 v166, s64, v152
	v_add_u32_e32 v171, s65, v152
	s_add_u32 s46, s22, s40
	ds_read_b128 v[154:157], v166
	ds_read_b128 v[158:161], v166 offset:1024
	ds_read_b128 v[162:165], v166 offset:2048
	ds_read_b128 v[166:169], v166 offset:3072
	ds_read_b128 v[172:175], v171
	ds_read_b128 v[176:179], v171 offset:1024
	ds_read_b128 v[180:183], v171 offset:2048
	ds_read_b128 v[184:187], v171 offset:3072
	s_addc_u32 s47, s23, s41
	s_add_u32 s46, s46, 0x100
	s_addc_u32 s47, s47, 0
	s_add_u32 s72, s67, s40
	s_addc_u32 s73, s68, s41
	s_cmpk_eq_i32 s40, 0x700
	s_cselect_b32 s49, s31, s47
	s_cselect_b32 s48, s69, s46
	s_cselect_b32 s47, s29, s73
	s_cselect_b32 s46, s70, s72
	v_lshl_add_u64 v[220:221], v[146:147], 0, s[40:41]
	s_add_i32 m0, s43, 0xc000
	ds_read_b128 v[188:191], v153
	ds_read_b128 v[192:195], v153 offset:1024
	ds_read_b128 v[196:199], v153 offset:2048
	ds_read_b128 v[200:203], v153 offset:3072
	ds_read_b128 v[204:207], v153 offset:4096
	ds_read_b128 v[208:211], v153 offset:5120
	ds_read_b128 v[212:215], v153 offset:6144
	ds_read_b128 v[216:219], v153 offset:7168
	global_load_lds_dwordx4 v[220:221], off
	v_lshl_add_u64 v[220:221], v[148:149], 0, s[40:41]
	s_add_i32 m0, s43, 0xe000
	s_nop 0
	global_load_lds_dwordx4 v[220:221], off
	s_waitcnt vmcnt(8)
	s_waitcnt lgkmcnt(0)
	s_setprio 1
	s_barrier
	v_mfma_f32_16x16x32_bf16 v[122:125], v[154:157], v[188:191], v[122:125]
	v_mfma_f32_16x16x32_bf16 v[118:121], v[162:165], v[188:191], v[118:121]
	v_mfma_f32_16x16x32_bf16 v[114:117], v[154:157], v[196:199], v[114:117]
	v_mfma_f32_16x16x32_bf16 v[98:101], v[162:165], v[196:199], v[98:101]
	v_mfma_f32_16x16x32_bf16 v[134:137], v[154:157], v[204:207], v[134:137]
	v_mfma_f32_16x16x32_bf16 v[102:105], v[162:165], v[204:207], v[102:105]
	v_mfma_f32_16x16x32_bf16 v[110:113], v[154:157], v[212:215], v[110:113]
	v_mfma_f32_16x16x32_bf16 v[86:89], v[162:165], v[212:215], v[86:89]
	v_mfma_f32_16x16x32_bf16 v[122:125], v[158:161], v[192:195], v[122:125]
	v_mfma_f32_16x16x32_bf16 v[118:121], v[166:169], v[192:195], v[118:121]
	v_mfma_f32_16x16x32_bf16 v[114:117], v[158:161], v[200:203], v[114:117]
	v_mfma_f32_16x16x32_bf16 v[98:101], v[166:169], v[200:203], v[98:101]
	v_mfma_f32_16x16x32_bf16 v[134:137], v[158:161], v[208:211], v[134:137]
	v_mfma_f32_16x16x32_bf16 v[102:105], v[166:169], v[208:211], v[102:105]
	v_mfma_f32_16x16x32_bf16 v[110:113], v[158:161], v[216:219], v[110:113]
	v_mfma_f32_16x16x32_bf16 v[86:89], v[166:169], v[216:219], v[86:89]
	v_mfma_f32_16x16x32_bf16 v[106:109], v[172:175], v[188:191], v[106:109]
	v_mfma_f32_16x16x32_bf16 v[94:97], v[180:183], v[188:191], v[94:97]
	v_mfma_f32_16x16x32_bf16 v[90:93], v[172:175], v[196:199], v[90:93]
	v_mfma_f32_16x16x32_bf16 v[82:85], v[180:183], v[196:199], v[82:85]
	v_mfma_f32_16x16x32_bf16 v[78:81], v[172:175], v[204:207], v[78:81]
	v_mfma_f32_16x16x32_bf16 v[74:77], v[180:183], v[204:207], v[74:77]
	v_mfma_f32_16x16x32_bf16 v[70:73], v[172:175], v[212:215], v[70:73]
	v_mfma_f32_16x16x32_bf16 v[66:69], v[180:183], v[212:215], v[66:69]
	v_mfma_f32_16x16x32_bf16 v[106:109], v[176:179], v[192:195], v[106:109]
	v_mfma_f32_16x16x32_bf16 v[94:97], v[184:187], v[192:195], v[94:97]
	v_mfma_f32_16x16x32_bf16 v[90:93], v[176:179], v[200:203], v[90:93]
	v_mfma_f32_16x16x32_bf16 v[82:85], v[184:187], v[200:203], v[82:85]
	v_mfma_f32_16x16x32_bf16 v[78:81], v[176:179], v[208:211], v[78:81]
	v_mfma_f32_16x16x32_bf16 v[74:77], v[184:187], v[208:211], v[74:77]
	v_mfma_f32_16x16x32_bf16 v[70:73], v[176:179], v[216:219], v[70:73]
	v_mfma_f32_16x16x32_bf16 v[66:69], v[184:187], v[216:219], v[66:69]
	s_barrier
	s_setprio 0
	s_add_i32 s72, s64, s33
	v_lshl_add_u64 v[220:221], s[46:47], 0, v[126:127]
	s_mov_b32 m0, s72
	ds_read_b128 v[188:191], v153 offset:16384
	ds_read_b128 v[192:195], v153 offset:17408
	ds_read_b128 v[196:199], v153 offset:18432
	ds_read_b128 v[200:203], v153 offset:19456
	ds_read_b128 v[204:207], v153 offset:20480
	ds_read_b128 v[208:211], v153 offset:21504
	ds_read_b128 v[212:215], v153 offset:22528
	ds_read_b128 v[216:219], v153 offset:23552
	global_load_lds_dwordx4 v[220:221], off
	s_add_i32 m0, s72, 0x2000
	s_add_u32 s72, s46, 0x40000
	v_lshl_add_u64 v[222:223], s[46:47], 0, v[132:133]
	s_addc_u32 s73, s47, 0
	s_add_i32 s74, s65, s33
	global_load_lds_dwordx4 v[222:223], off
	v_lshl_add_u64 v[224:225], s[72:73], 0, v[126:127]
	s_mov_b32 m0, s74
	v_lshl_add_u64 v[226:227], s[48:49], 0, v[130:131]
	global_load_lds_dwordx4 v[224:225], off
	v_lshl_add_u64 v[224:225], s[72:73], 0, v[132:133]
	s_add_i32 m0, s74, 0x2000
	s_nop 0
	global_load_lds_dwordx4 v[224:225], off
	v_lshl_add_u64 v[224:225], s[48:49], 0, v[128:129]
	s_mov_b32 m0, s43
	s_nop 0
	global_load_lds_dwordx4 v[224:225], off
	s_mov_b32 m0, s44
	s_nop 0
	global_load_lds_dwordx4 v[226:227], off
	s_waitcnt vmcnt(8)
	s_waitcnt lgkmcnt(0)
	s_setprio 1
	s_barrier
; #define PG8_STAGE(bufoff, gbase, voff) do { _Pragma("unroll") for (int _i = 0; _i < 2; ++_i) \
;         __builtin_amdgcn_global_load_lds((const unsigned*)((const char*)(gbase) + (voff)[_i]), (PG8_LAS unsigned*)(lds + (bufoff) + ldsw + _i * 8192), 16, 0, 0); } while (0)
; #define PG8_LDA(dst, b, h) do { _Pragma("unroll") for (int m = 0; m < 4; ++m) _Pragma("unroll") for (int k = 0; k < 2; ++k) dst[m][k] = *(const PG8_LAS bf16x8*)(lds + PG8_SA(b, h) + aoff + m * 2048 + k * 1024); } while (0)
; #define PG8_LDB(dst, b, h) do { _Pragma("unroll") for (int n = 0; n < 2; ++n) _Pragma("unroll") for (int k = 0; k < 2; ++k) dst[n][k] = *(const PG8_LAS bf16x8*)(lds + PG8_SB(b, h) + boff + n * 2048 + k * 1024); } while (0)
; #define PG8_MMA(ai, bj, At, Bt) do { __builtin_amdgcn_s_setprio(1); _Pragma("unroll") for (int m = 0; m < 4; ++m) _Pragma("unroll") for (int n = 0; n < 2; ++n) _Pragma("unroll") for (int k = 0; k < 2; ++k) \
;         acc[ai][bj][m][n] = __builtin_amdgcn_mfma_f32_16x16x32_bf16(Bt[n][k], At[m][k], acc[ai][bj][m][n], 0, 0, 0); __builtin_amdgcn_s_setprio(0); } while (0)
; #define PG8_WAIT_V(n) asm volatile("s_waitcnt vmcnt(" #n ")" ::: "memory")
; #define PG8_WAIT_L(n) asm volatile("s_waitcnt lgkmcnt(" #n ")" ::: "memory")
; #define PG8_BAR __builtin_amdgcn_s_barrier()
; #define PG8_SCHED __builtin_amdgcn_sched_barrier(0)
; template <class Epi, class Sched, bool ALIGN_EPI = false, bool SP2 = false>
; __device__ __forceinline__ void gemm_phase(PG8_LAS unsigned char* lds, const Gemm g, const Sched& S, const Epi& E) {
;     ...
;             PG8_WAIT_V(8); PG8_WAIT_L(0); PG8_BAR; PG8_MMA(1, 0, At, B0); PG8_MMA(1, 1, At, B1); PG8_BAR; PG8_SCHED;
;             PG8_LDB(B0, 1, 0); PG8_LDB(B1, 1, 1); PG8_SCHED; PG8_LDA(At, 1, 0); PG8_STAGE(PG8_SA(0, 1), a2 + hstepA, voffA);
;             PG8_WAIT_V(8); PG8_WAIT_L(0); PG8_BAR; PG8_MMA(0, 0, At, B0); PG8_MMA(0, 1, At, B1); PG8_BAR; PG8_SCHED;
	v_mfma_f32_16x16x32_bf16 v[62:65], v[154:157], v[188:191], v[62:65]
	v_mfma_f32_16x16x32_bf16 v[58:61], v[162:165], v[188:191], v[58:61]
	v_mfma_f32_16x16x32_bf16 v[54:57], v[154:157], v[196:199], v[54:57]
	v_mfma_f32_16x16x32_bf16 v[46:49], v[162:165], v[196:199], v[46:49]
	v_mfma_f32_16x16x32_bf16 v[38:41], v[154:157], v[204:207], v[38:41]
	v_mfma_f32_16x16x32_bf16 v[30:33], v[162:165], v[204:207], v[30:33]
	v_mfma_f32_16x16x32_bf16 v[14:17], v[154:157], v[212:215], v[14:17]
	v_mfma_f32_16x16x32_bf16 v[10:13], v[162:165], v[212:215], v[10:13]
	v_mfma_f32_16x16x32_bf16 v[62:65], v[158:161], v[192:195], v[62:65]
	v_mfma_f32_16x16x32_bf16 v[58:61], v[166:169], v[192:195], v[58:61]
	v_mfma_f32_16x16x32_bf16 v[54:57], v[158:161], v[200:203], v[54:57]
	v_mfma_f32_16x16x32_bf16 v[46:49], v[166:169], v[200:203], v[46:49]
	v_mfma_f32_16x16x32_bf16 v[38:41], v[158:161], v[208:211], v[38:41]
	v_mfma_f32_16x16x32_bf16 v[30:33], v[166:169], v[208:211], v[30:33]
	v_mfma_f32_16x16x32_bf16 v[14:17], v[158:161], v[216:219], v[14:17]
	v_mfma_f32_16x16x32_bf16 v[10:13], v[166:169], v[216:219], v[10:13]
	v_mfma_f32_16x16x32_bf16 v[50:53], v[172:175], v[188:191], v[50:53]
	v_mfma_f32_16x16x32_bf16 v[42:45], v[180:183], v[188:191], v[42:45]
	v_mfma_f32_16x16x32_bf16 v[34:37], v[172:175], v[196:199], v[34:37]
	v_mfma_f32_16x16x32_bf16 v[26:29], v[180:183], v[196:199], v[26:29]
	v_mfma_f32_16x16x32_bf16 v[22:25], v[172:175], v[204:207], v[22:25]
	v_mfma_f32_16x16x32_bf16 v[18:21], v[180:183], v[204:207], v[18:21]
	v_mfma_f32_16x16x32_bf16 v[6:9], v[172:175], v[212:215], v[6:9]
	v_mfma_f32_16x16x32_bf16 v[2:5], v[180:183], v[212:215], v[2:5]
	v_mfma_f32_16x16x32_bf16 v[50:53], v[176:179], v[192:195], v[50:53]
	v_mfma_f32_16x16x32_bf16 v[42:45], v[184:187], v[192:195], v[42:45]
	v_mfma_f32_16x16x32_bf16 v[34:37], v[176:179], v[200:203], v[34:37]
	v_mfma_f32_16x16x32_bf16 v[26:29], v[184:187], v[200:203], v[26:29]
	v_mfma_f32_16x16x32_bf16 v[22:25], v[176:179], v[208:211], v[22:25]
	v_mfma_f32_16x16x32_bf16 v[18:21], v[184:187], v[208:211], v[18:21]
	v_mfma_f32_16x16x32_bf16 v[6:9], v[176:179], v[216:219], v[6:9]
	v_mfma_f32_16x16x32_bf16 v[2:5], v[184:187], v[216:219], v[2:5]
	s_barrier
	s_setprio 0
	s_add_i32 s72, 0, 0x18000
	s_add_i32 s73, 0, 0x1c000
	v_add_u32_e32 v166, s72, v152
	v_add_u32_e32 v171, s73, v152
	ds_read_b128 v[154:157], v166
	ds_read_b128 v[158:161], v166 offset:1024
	ds_read_b128 v[162:165], v166 offset:2048
	ds_read_b128 v[166:169], v166 offset:3072
	ds_read_b128 v[172:175], v171
	ds_read_b128 v[176:179], v171 offset:1024
	ds_read_b128 v[180:183], v171 offset:2048
	ds_read_b128 v[184:187], v171 offset:3072
	s_add_u32 s48, s48, 0x40000
	s_addc_u32 s49, s49, 0
	s_mov_b32 m0, s45
	v_lshl_add_u64 v[228:229], s[48:49], 0, v[128:129]
	ds_read_b128 v[188:191], v153 offset:32768
	ds_read_b128 v[192:195], v153 offset:33792
	ds_read_b128 v[196:199], v153 offset:34816
	ds_read_b128 v[200:203], v153 offset:35840
	ds_read_b128 v[204:207], v153 offset:36864
	ds_read_b128 v[208:211], v153 offset:37888
	ds_read_b128 v[212:215], v153 offset:38912
	ds_read_b128 v[216:219], v153 offset:39936
	global_load_lds_dwordx4 v[228:229], off
	v_lshl_add_u64 v[228:229], s[48:49], 0, v[130:131]
	s_mov_b32 m0, s50
	s_nop 0
	global_load_lds_dwordx4 v[228:229], off
	s_waitcnt vmcnt(8)
	s_waitcnt lgkmcnt(0)
	s_setprio 1
	s_barrier
	v_mfma_f32_16x16x32_bf16 v[122:125], v[154:157], v[188:191], v[122:125]
	v_mfma_f32_16x16x32_bf16 v[118:121], v[162:165], v[188:191], v[118:121]
	v_mfma_f32_16x16x32_bf16 v[114:117], v[154:157], v[196:199], v[114:117]
	v_mfma_f32_16x16x32_bf16 v[98:101], v[162:165], v[196:199], v[98:101]
	v_mfma_f32_16x16x32_bf16 v[134:137], v[154:157], v[204:207], v[134:137]
	v_mfma_f32_16x16x32_bf16 v[102:105], v[162:165], v[204:207], v[102:105]
	v_mfma_f32_16x16x32_bf16 v[110:113], v[154:157], v[212:215], v[110:113]
	v_mfma_f32_16x16x32_bf16 v[86:89], v[162:165], v[212:215], v[86:89]
	v_mfma_f32_16x16x32_bf16 v[122:125], v[158:161], v[192:195], v[122:125]
	v_mfma_f32_16x16x32_bf16 v[118:121], v[166:169], v[192:195], v[118:121]
	v_mfma_f32_16x16x32_bf16 v[114:117], v[158:161], v[200:203], v[114:117]
	v_mfma_f32_16x16x32_bf16 v[98:101], v[166:169], v[200:203], v[98:101]
	v_mfma_f32_16x16x32_bf16 v[134:137], v[158:161], v[208:211], v[134:137]
	v_mfma_f32_16x16x32_bf16 v[102:105], v[166:169], v[208:211], v[102:105]
	v_mfma_f32_16x16x32_bf16 v[110:113], v[158:161], v[216:219], v[110:113]
	v_mfma_f32_16x16x32_bf16 v[86:89], v[166:169], v[216:219], v[86:89]
	v_mfma_f32_16x16x32_bf16 v[106:109], v[172:175], v[188:191], v[106:109]
	v_mfma_f32_16x16x32_bf16 v[94:97], v[180:183], v[188:191], v[94:97]
	v_mfma_f32_16x16x32_bf16 v[90:93], v[172:175], v[196:199], v[90:93]
	v_mfma_f32_16x16x32_bf16 v[82:85], v[180:183], v[196:199], v[82:85]
	v_mfma_f32_16x16x32_bf16 v[78:81], v[172:175], v[204:207], v[78:81]
	v_mfma_f32_16x16x32_bf16 v[74:77], v[180:183], v[204:207], v[74:77]
	v_mfma_f32_16x16x32_bf16 v[70:73], v[172:175], v[212:215], v[70:73]
	v_mfma_f32_16x16x32_bf16 v[66:69], v[180:183], v[212:215], v[66:69]
	v_mfma_f32_16x16x32_bf16 v[106:109], v[176:179], v[192:195], v[106:109]
	v_mfma_f32_16x16x32_bf16 v[94:97], v[184:187], v[192:195], v[94:97]
	v_mfma_f32_16x16x32_bf16 v[90:93], v[176:179], v[200:203], v[90:93]
	v_mfma_f32_16x16x32_bf16 v[82:85], v[184:187], v[200:203], v[82:85]
	v_mfma_f32_16x16x32_bf16 v[78:81], v[176:179], v[208:211], v[78:81]
	v_mfma_f32_16x16x32_bf16 v[74:77], v[184:187], v[208:211], v[74:77]
	v_mfma_f32_16x16x32_bf16 v[70:73], v[176:179], v[216:219], v[70:73]
	v_mfma_f32_16x16x32_bf16 v[66:69], v[184:187], v[216:219], v[66:69]
	s_barrier
; #define PG8_STAGE(bufoff, gbase, voff) do { _Pragma("unroll") for (int _i = 0; _i < 2; ++_i) \
;         __builtin_amdgcn_global_load_lds((const unsigned*)((const char*)(gbase) + (voff)[_i]), (PG8_LAS unsigned*)(lds + (bufoff) + ldsw + _i * 8192), 16, 0, 0); } while (0)
; #define PG8_LDA(dst, b, h) do { _Pragma("unroll") for (int m = 0; m < 4; ++m) _Pragma("unroll") for (int k = 0; k < 2; ++k) dst[m][k] = *(const PG8_LAS bf16x8*)(lds + PG8_SA(b, h) + aoff + m * 2048 + k * 1024); } while (0)
; #define PG8_MMA(ai, bj, At, Bt) do { __builtin_amdgcn_s_setprio(1); _Pragma("unroll") for (int m = 0; m < 4; ++m) _Pragma("unroll") for (int n = 0; n < 2; ++n) _Pragma("unroll") for (int k = 0; k < 2; ++k) \
;         acc[ai][bj][m][n] = __builtin_amdgcn_mfma_f32_16x16x32_bf16(Bt[n][k], At[m][k], acc[ai][bj][m][n], 0, 0, 0); __builtin_amdgcn_s_setprio(0); } while (0)
; #define PG8_WAIT_V(n) asm volatile("s_waitcnt vmcnt(" #n ")" ::: "memory")
; #define PG8_WAIT_L(n) asm volatile("s_waitcnt lgkmcnt(" #n ")" ::: "memory")
; #define PG8_BAR __builtin_amdgcn_s_barrier()
; #define PG8_SCHED __builtin_amdgcn_sched_barrier(0)
; template <class Epi, class Sched, bool ALIGN_EPI = false, bool SP2 = false>
; __device__ __forceinline__ void gemm_phase(PG8_LAS unsigned char* lds, const Gemm g, const Sched& S, const Epi& E) {
;     ...
;         for (int t = 0; t < nt; t += 2) {
;             const bool last = (t == nt - 2);
;             const char* a1 = cA + (size_t)(t + 1) * kstepA;
;             const char* a2 = last ? nA : cA + (size_t)(t + 2) * kstepA; const char* b2 = last ? nB : cB + (size_t)(t + 2) * kstep;
;     ...
;             PG8_LDA(At, 1, 1); PG8_STAGE(PG8_SB(1, 0), b3, voffB); PG8_STAGE(PG8_SB(1, 1), b3 + hstepB, voffB); PG8_STAGE(PG8_SA(1, 0), a3, voffA);
;             PG8_WAIT_V(8); PG8_WAIT_L(0); PG8_BAR; PG8_MMA(1, 0, At, B0); PG8_MMA(1, 1, At, B1); PG8_BAR; PG8_SCHED;
	s_setprio 0
	s_add_i32 s48, s72, s33
	v_lshl_add_u64 v[220:221], v[220:221], 0, s[24:25]
	s_mov_b32 m0, s48
	ds_read_b128 v[188:191], v153 offset:49152
	ds_read_b128 v[192:195], v153 offset:50176
	ds_read_b128 v[196:199], v153 offset:51200
	ds_read_b128 v[200:203], v153 offset:52224
	ds_read_b128 v[204:207], v153 offset:53248
	ds_read_b128 v[208:211], v153 offset:54272
	ds_read_b128 v[212:215], v153 offset:55296
	ds_read_b128 v[216:219], v153 offset:56320
	global_load_lds_dwordx4 v[220:221], off
	s_add_i32 m0, s48, 0x2000
	s_add_u32 s46, s46, 0x40080
	v_lshl_add_u64 v[220:221], v[222:223], 0, s[24:25]
	s_addc_u32 s47, s47, 0
	s_add_i32 s48, s73, s33
	global_load_lds_dwordx4 v[220:221], off
	v_lshl_add_u64 v[220:221], s[46:47], 0, v[126:127]
	s_mov_b32 m0, s48
	s_nop 0
	global_load_lds_dwordx4 v[220:221], off
	v_lshl_add_u64 v[220:221], s[46:47], 0, v[132:133]
	s_add_i32 m0, s48, 0x2000
	s_nop 0
	global_load_lds_dwordx4 v[220:221], off
	v_lshl_add_u64 v[220:221], v[224:225], 0, s[24:25]
	s_mov_b32 m0, s62
	s_nop 0
	global_load_lds_dwordx4 v[220:221], off
	v_lshl_add_u64 v[220:221], v[226:227], 0, s[24:25]
	s_mov_b32 m0, s63
	s_nop 0
	global_load_lds_dwordx4 v[220:221], off
	s_waitcnt vmcnt(8)
	s_waitcnt lgkmcnt(0)
	s_setprio 1
	s_barrier
	v_mfma_f32_16x16x32_bf16 v[62:65], v[154:157], v[188:191], v[62:65]
	v_mfma_f32_16x16x32_bf16 v[58:61], v[162:165], v[188:191], v[58:61]
	v_mfma_f32_16x16x32_bf16 v[54:57], v[154:157], v[196:199], v[54:57]
	v_mfma_f32_16x16x32_bf16 v[46:49], v[162:165], v[196:199], v[46:49]
	v_mfma_f32_16x16x32_bf16 v[38:41], v[154:157], v[204:207], v[38:41]
	v_mfma_f32_16x16x32_bf16 v[30:33], v[162:165], v[204:207], v[30:33]
	v_mfma_f32_16x16x32_bf16 v[14:17], v[154:157], v[212:215], v[14:17]
	v_mfma_f32_16x16x32_bf16 v[10:13], v[162:165], v[212:215], v[10:13]
	v_mfma_f32_16x16x32_bf16 v[62:65], v[158:161], v[192:195], v[62:65]
	v_mfma_f32_16x16x32_bf16 v[58:61], v[166:169], v[192:195], v[58:61]
	v_mfma_f32_16x16x32_bf16 v[54:57], v[158:161], v[200:203], v[54:57]
	v_mfma_f32_16x16x32_bf16 v[46:49], v[166:169], v[200:203], v[46:49]
	v_mfma_f32_16x16x32_bf16 v[38:41], v[158:161], v[208:211], v[38:41]
	v_mfma_f32_16x16x32_bf16 v[30:33], v[166:169], v[208:211], v[30:33]
	v_mfma_f32_16x16x32_bf16 v[14:17], v[158:161], v[216:219], v[14:17]
	v_mfma_f32_16x16x32_bf16 v[10:13], v[166:169], v[216:219], v[10:13]
	v_mfma_f32_16x16x32_bf16 v[50:53], v[172:175], v[188:191], v[50:53]
	v_mfma_f32_16x16x32_bf16 v[42:45], v[180:183], v[188:191], v[42:45]
	v_mfma_f32_16x16x32_bf16 v[34:37], v[172:175], v[196:199], v[34:37]
	v_mfma_f32_16x16x32_bf16 v[26:29], v[180:183], v[196:199], v[26:29]
	v_mfma_f32_16x16x32_bf16 v[22:25], v[172:175], v[204:207], v[22:25]
	v_mfma_f32_16x16x32_bf16 v[18:21], v[180:183], v[204:207], v[18:21]
	v_mfma_f32_16x16x32_bf16 v[6:9], v[172:175], v[212:215], v[6:9]
	v_mfma_f32_16x16x32_bf16 v[2:5], v[180:183], v[212:215], v[2:5]
	v_mfma_f32_16x16x32_bf16 v[50:53], v[176:179], v[192:195], v[50:53]
	v_mfma_f32_16x16x32_bf16 v[42:45], v[184:187], v[192:195], v[42:45]
	v_mfma_f32_16x16x32_bf16 v[34:37], v[176:179], v[200:203], v[34:37]
	v_mfma_f32_16x16x32_bf16 v[26:29], v[184:187], v[200:203], v[26:29]
	v_mfma_f32_16x16x32_bf16 v[22:25], v[176:179], v[208:211], v[22:25]
	v_mfma_f32_16x16x32_bf16 v[18:21], v[184:187], v[208:211], v[18:21]
	v_mfma_f32_16x16x32_bf16 v[6:9], v[176:179], v[216:219], v[6:9]
	v_mfma_f32_16x16x32_bf16 v[2:5], v[184:187], v[216:219], v[2:5]
	s_barrier
	s_setprio 0
	s_add_i32 s71, s71, 2
	s_add_u32 s40, s40, 0x100
	s_addc_u32 s41, s41, 0
	s_cmp_gt_u32 s71, 11
	s_cbranch_scc0 .LBB0_1088
	s_cmp_gt_u32 s71, 13
	s_cbranch_scc1 .Lpeel_p6_done
	s_and_b64 vcc, exec, s[6:7]
	s_cbranch_vccnz .LBB0_1088
	v_add_u32_e32 v166, s64, v152
	v_add_u32_e32 v171, s65, v152
	s_add_u32 s46, s22, s40
	ds_read_b128 v[154:157], v166
	ds_read_b128 v[158:161], v166 offset:1024
	ds_read_b128 v[162:165], v166 offset:2048
	ds_read_b128 v[166:169], v166 offset:3072
	ds_read_b128 v[172:175], v171
	ds_read_b128 v[176:179], v171 offset:1024
	ds_read_b128 v[180:183], v171 offset:2048
	ds_read_b128 v[184:187], v171 offset:3072
	s_addc_u32 s47, s23, s41
	s_add_u32 s46, s46, 0x100
	s_addc_u32 s47, s47, 0
	s_add_u32 s72, s67, s40
	s_addc_u32 s73, s68, s41
	s_cmpk_eq_i32 s40, 0x700
	s_cselect_b32 s49, s31, s47
	s_cselect_b32 s48, s69, s46
	s_cselect_b32 s47, s29, s73
	s_cselect_b32 s46, s70, s72
	v_lshl_add_u64 v[220:221], v[146:147], 0, s[40:41]
	s_add_i32 m0, s43, 0xc000
	ds_read_b128 v[188:191], v153
	ds_read_b128 v[192:195], v153 offset:1024
	ds_read_b128 v[196:199], v153 offset:2048
	ds_read_b128 v[200:203], v153 offset:3072
	ds_read_b128 v[204:207], v153 offset:4096
	ds_read_b128 v[208:211], v153 offset:5120
	ds_read_b128 v[212:215], v153 offset:6144
	ds_read_b128 v[216:219], v153 offset:7168
	global_load_lds_dwordx4 v[220:221], off
	v_lshl_add_u64 v[220:221], v[148:149], 0, s[40:41]
	s_add_i32 m0, s43, 0xe000
	s_nop 0
	global_load_lds_dwordx4 v[220:221], off
	s_waitcnt vmcnt(8)
	s_waitcnt lgkmcnt(0)
	s_setprio 1
	s_barrier
; #define PG8_STAGE(bufoff, gbase, voff) do { _Pragma("unroll") for (int _i = 0; _i < 2; ++_i) \
;         __builtin_amdgcn_global_load_lds((const unsigned*)((const char*)(gbase) + (voff)[_i]), (PG8_LAS unsigned*)(lds + (bufoff) + ldsw + _i * 8192), 16, 0, 0); } while (0)
; #define PG8_LDA(dst, b, h) do { _Pragma("unroll") for (int m = 0; m < 4; ++m) _Pragma("unroll") for (int k = 0; k < 2; ++k) dst[m][k] = *(const PG8_LAS bf16x8*)(lds + PG8_SA(b, h) + aoff + m * 2048 + k * 1024); } while (0)
; #define PG8_LDB(dst, b, h) do { _Pragma("unroll") for (int n = 0; n < 2; ++n) _Pragma("unroll") for (int k = 0; k < 2; ++k) dst[n][k] = *(const PG8_LAS bf16x8*)(lds + PG8_SB(b, h) + boff + n * 2048 + k * 1024); } while (0)
; #define PG8_MMA(ai, bj, At, Bt) do { __builtin_amdgcn_s_setprio(1); _Pragma("unroll") for (int m = 0; m < 4; ++m) _Pragma("unroll") for (int n = 0; n < 2; ++n) _Pragma("unroll") for (int k = 0; k < 2; ++k) \
;         acc[ai][bj][m][n] = __builtin_amdgcn_mfma_f32_16x16x32_bf16(Bt[n][k], At[m][k], acc[ai][bj][m][n], 0, 0, 0); __builtin_amdgcn_s_setprio(0); } while (0)
; #define PG8_WAIT_V(n) asm volatile("s_waitcnt vmcnt(" #n ")" ::: "memory")
; #define PG8_WAIT_L(n) asm volatile("s_waitcnt lgkmcnt(" #n ")" ::: "memory")
; #define PG8_BAR __builtin_amdgcn_s_barrier()
; #define PG8_SCHED __builtin_amdgcn_sched_barrier(0)
; template <class Epi, class Sched, bool ALIGN_EPI = false, bool SP2 = false>
; __device__ __forceinline__ void gemm_phase(PG8_LAS unsigned char* lds, const Gemm g, const Sched& S, const Epi& E) {
;     ...
;             PG8_LDB(B0, 0, 0); PG8_LDB(B1, 0, 1); PG8_SCHED; PG8_LDA(At, 0, 0); PG8_STAGE(PG8_SA(1, 1), a1 + hstepA, voffA);
;             PG8_WAIT_V(8); PG8_WAIT_L(0); PG8_BAR; PG8_MMA(0, 0, At, B0); PG8_MMA(0, 1, At, B1); PG8_BAR; PG8_SCHED;
;             PG8_LDA(At, 0, 1); PG8_STAGE(PG8_SB(0, 0), b2, voffB); PG8_STAGE(PG8_SB(0, 1), b2 + hstepB, voffB); PG8_STAGE(PG8_SA(0, 0), a2, voffA);
;             PG8_WAIT_V(8); PG8_WAIT_L(0); PG8_BAR; PG8_MMA(1, 0, At, B0); PG8_MMA(1, 1, At, B1); PG8_BAR; PG8_SCHED;
	v_mfma_f32_16x16x32_bf16 v[122:125], v[154:157], v[188:191], v[122:125]
	v_mfma_f32_16x16x32_bf16 v[118:121], v[162:165], v[188:191], v[118:121]
	v_mfma_f32_16x16x32_bf16 v[114:117], v[154:157], v[196:199], v[114:117]
	v_mfma_f32_16x16x32_bf16 v[98:101], v[162:165], v[196:199], v[98:101]
	v_mfma_f32_16x16x32_bf16 v[134:137], v[154:157], v[204:207], v[134:137]
	v_mfma_f32_16x16x32_bf16 v[102:105], v[162:165], v[204:207], v[102:105]
	v_mfma_f32_16x16x32_bf16 v[110:113], v[154:157], v[212:215], v[110:113]
	v_mfma_f32_16x16x32_bf16 v[86:89], v[162:165], v[212:215], v[86:89]
	v_mfma_f32_16x16x32_bf16 v[122:125], v[158:161], v[192:195], v[122:125]
	v_mfma_f32_16x16x32_bf16 v[118:121], v[166:169], v[192:195], v[118:121]
	v_mfma_f32_16x16x32_bf16 v[114:117], v[158:161], v[200:203], v[114:117]
	v_mfma_f32_16x16x32_bf16 v[98:101], v[166:169], v[200:203], v[98:101]
	v_mfma_f32_16x16x32_bf16 v[134:137], v[158:161], v[208:211], v[134:137]
	v_mfma_f32_16x16x32_bf16 v[102:105], v[166:169], v[208:211], v[102:105]
	v_mfma_f32_16x16x32_bf16 v[110:113], v[158:161], v[216:219], v[110:113]
	v_mfma_f32_16x16x32_bf16 v[86:89], v[166:169], v[216:219], v[86:89]
	v_mfma_f32_16x16x32_bf16 v[106:109], v[172:175], v[188:191], v[106:109]
	v_mfma_f32_16x16x32_bf16 v[94:97], v[180:183], v[188:191], v[94:97]
	v_mfma_f32_16x16x32_bf16 v[90:93], v[172:175], v[196:199], v[90:93]
	v_mfma_f32_16x16x32_bf16 v[82:85], v[180:183], v[196:199], v[82:85]
	v_mfma_f32_16x16x32_bf16 v[78:81], v[172:175], v[204:207], v[78:81]
	v_mfma_f32_16x16x32_bf16 v[74:77], v[180:183], v[204:207], v[74:77]
	v_mfma_f32_16x16x32_bf16 v[70:73], v[172:175], v[212:215], v[70:73]
	v_mfma_f32_16x16x32_bf16 v[66:69], v[180:183], v[212:215], v[66:69]
	v_mfma_f32_16x16x32_bf16 v[106:109], v[176:179], v[192:195], v[106:109]
	v_mfma_f32_16x16x32_bf16 v[94:97], v[184:187], v[192:195], v[94:97]
	v_mfma_f32_16x16x32_bf16 v[90:93], v[176:179], v[200:203], v[90:93]
	v_mfma_f32_16x16x32_bf16 v[82:85], v[184:187], v[200:203], v[82:85]
	v_mfma_f32_16x16x32_bf16 v[78:81], v[176:179], v[208:211], v[78:81]
	v_mfma_f32_16x16x32_bf16 v[74:77], v[184:187], v[208:211], v[74:77]
	v_mfma_f32_16x16x32_bf16 v[70:73], v[176:179], v[216:219], v[70:73]
	v_mfma_f32_16x16x32_bf16 v[66:69], v[184:187], v[216:219], v[66:69]
	s_barrier
	s_setprio 0
	s_add_i32 s72, s64, s33
	v_lshl_add_u64 v[220:221], s[46:47], 0, v[126:127]
	s_mov_b32 m0, s72
	ds_read_b128 v[188:191], v153 offset:16384
	ds_read_b128 v[192:195], v153 offset:17408
	ds_read_b128 v[196:199], v153 offset:18432
	ds_read_b128 v[200:203], v153 offset:19456
	ds_read_b128 v[204:207], v153 offset:20480
	ds_read_b128 v[208:211], v153 offset:21504
	ds_read_b128 v[212:215], v153 offset:22528
	ds_read_b128 v[216:219], v153 offset:23552
	s_add_i32 m0, s72, 0x2000
	s_add_u32 s72, s46, 0x40000
	v_lshl_add_u64 v[222:223], s[46:47], 0, v[132:133]
	s_addc_u32 s73, s47, 0
	s_add_i32 s74, s65, s33
	v_lshl_add_u64 v[224:225], s[72:73], 0, v[126:127]
	s_mov_b32 m0, s74
	v_lshl_add_u64 v[226:227], s[48:49], 0, v[130:131]
	v_lshl_add_u64 v[224:225], s[72:73], 0, v[132:133]
	s_add_i32 m0, s74, 0x2000
	s_nop 0
	v_lshl_add_u64 v[224:225], s[48:49], 0, v[128:129]
	s_mov_b32 m0, s43
	s_nop 0
	s_mov_b32 m0, s44
	s_nop 0
	s_waitcnt vmcnt(2)
	s_waitcnt lgkmcnt(0)
	s_setprio 1
	s_barrier
	v_mfma_f32_16x16x32_bf16 v[62:65], v[154:157], v[188:191], v[62:65]
	v_mfma_f32_16x16x32_bf16 v[58:61], v[162:165], v[188:191], v[58:61]
	v_mfma_f32_16x16x32_bf16 v[54:57], v[154:157], v[196:199], v[54:57]
	v_mfma_f32_16x16x32_bf16 v[46:49], v[162:165], v[196:199], v[46:49]
	v_mfma_f32_16x16x32_bf16 v[38:41], v[154:157], v[204:207], v[38:41]
	v_mfma_f32_16x16x32_bf16 v[30:33], v[162:165], v[204:207], v[30:33]
	v_mfma_f32_16x16x32_bf16 v[14:17], v[154:157], v[212:215], v[14:17]
	v_mfma_f32_16x16x32_bf16 v[10:13], v[162:165], v[212:215], v[10:13]
	v_mfma_f32_16x16x32_bf16 v[62:65], v[158:161], v[192:195], v[62:65]
	v_mfma_f32_16x16x32_bf16 v[58:61], v[166:169], v[192:195], v[58:61]
	v_mfma_f32_16x16x32_bf16 v[54:57], v[158:161], v[200:203], v[54:57]
	v_mfma_f32_16x16x32_bf16 v[46:49], v[166:169], v[200:203], v[46:49]
	v_mfma_f32_16x16x32_bf16 v[38:41], v[158:161], v[208:211], v[38:41]
	v_mfma_f32_16x16x32_bf16 v[30:33], v[166:169], v[208:211], v[30:33]
	v_mfma_f32_16x16x32_bf16 v[14:17], v[158:161], v[216:219], v[14:17]
	v_mfma_f32_16x16x32_bf16 v[10:13], v[166:169], v[216:219], v[10:13]
	v_mfma_f32_16x16x32_bf16 v[50:53], v[172:175], v[188:191], v[50:53]
	v_mfma_f32_16x16x32_bf16 v[42:45], v[180:183], v[188:191], v[42:45]
	v_mfma_f32_16x16x32_bf16 v[34:37], v[172:175], v[196:199], v[34:37]
	v_mfma_f32_16x16x32_bf16 v[26:29], v[180:183], v[196:199], v[26:29]
	v_mfma_f32_16x16x32_bf16 v[22:25], v[172:175], v[204:207], v[22:25]
	v_mfma_f32_16x16x32_bf16 v[18:21], v[180:183], v[204:207], v[18:21]
	v_mfma_f32_16x16x32_bf16 v[6:9], v[172:175], v[212:215], v[6:9]
	v_mfma_f32_16x16x32_bf16 v[2:5], v[180:183], v[212:215], v[2:5]
	v_mfma_f32_16x16x32_bf16 v[50:53], v[176:179], v[192:195], v[50:53]
	v_mfma_f32_16x16x32_bf16 v[42:45], v[184:187], v[192:195], v[42:45]
	v_mfma_f32_16x16x32_bf16 v[34:37], v[176:179], v[200:203], v[34:37]
	v_mfma_f32_16x16x32_bf16 v[26:29], v[184:187], v[200:203], v[26:29]
	v_mfma_f32_16x16x32_bf16 v[22:25], v[176:179], v[208:211], v[22:25]
	v_mfma_f32_16x16x32_bf16 v[18:21], v[184:187], v[208:211], v[18:21]
	v_mfma_f32_16x16x32_bf16 v[6:9], v[176:179], v[216:219], v[6:9]
	v_mfma_f32_16x16x32_bf16 v[2:5], v[184:187], v[216:219], v[2:5]
	s_barrier
; #define PG8_STAGE(bufoff, gbase, voff) do { _Pragma("unroll") for (int _i = 0; _i < 2; ++_i) \
;         __builtin_amdgcn_global_load_lds((const unsigned*)((const char*)(gbase) + (voff)[_i]), (PG8_LAS unsigned*)(lds + (bufoff) + ldsw + _i * 8192), 16, 0, 0); } while (0)
; #define PG8_LDA(dst, b, h) do { _Pragma("unroll") for (int m = 0; m < 4; ++m) _Pragma("unroll") for (int k = 0; k < 2; ++k) dst[m][k] = *(const PG8_LAS bf16x8*)(lds + PG8_SA(b, h) + aoff + m * 2048 + k * 1024); } while (0)
; #define PG8_LDB(dst, b, h) do { _Pragma("unroll") for (int n = 0; n < 2; ++n) _Pragma("unroll") for (int k = 0; k < 2; ++k) dst[n][k] = *(const PG8_LAS bf16x8*)(lds + PG8_SB(b, h) + boff + n * 2048 + k * 1024); } while (0)
; #define PG8_MMA(ai, bj, At, Bt) do { __builtin_amdgcn_s_setprio(1); _Pragma("unroll") for (int m = 0; m < 4; ++m) _Pragma("unroll") for (int n = 0; n < 2; ++n) _Pragma("unroll") for (int k = 0; k < 2; ++k) \
;         acc[ai][bj][m][n] = __builtin_amdgcn_mfma_f32_16x16x32_bf16(Bt[n][k], At[m][k], acc[ai][bj][m][n], 0, 0, 0); __builtin_amdgcn_s_setprio(0); } while (0)
; #define PG8_WAIT_V(n) asm volatile("s_waitcnt vmcnt(" #n ")" ::: "memory")
; #define PG8_WAIT_L(n) asm volatile("s_waitcnt lgkmcnt(" #n ")" ::: "memory")
; #define PG8_BAR __builtin_amdgcn_s_barrier()
; #define PG8_SCHED __builtin_amdgcn_sched_barrier(0)
; template <class Epi, class Sched, bool ALIGN_EPI = false, bool SP2 = false>
; __device__ __forceinline__ void gemm_phase(PG8_LAS unsigned char* lds, const Gemm g, const Sched& S, const Epi& E) {
;     ...
;             PG8_LDB(B0, 1, 0); PG8_LDB(B1, 1, 1); PG8_SCHED; PG8_LDA(At, 1, 0); PG8_STAGE(PG8_SA(0, 1), a2 + hstepA, voffA);
;             PG8_WAIT_V(8); PG8_WAIT_L(0); PG8_BAR; PG8_MMA(0, 0, At, B0); PG8_MMA(0, 1, At, B1); PG8_BAR; PG8_SCHED;
;             PG8_LDA(At, 1, 1); PG8_STAGE(PG8_SB(1, 0), b3, voffB); PG8_STAGE(PG8_SB(1, 1), b3 + hstepB, voffB); PG8_STAGE(PG8_SA(1, 0), a3, voffA);
;             PG8_WAIT_V(8); PG8_WAIT_L(0); PG8_BAR; PG8_MMA(1, 0, At, B0); PG8_MMA(1, 1, At, B1); PG8_BAR; PG8_SCHED;
	s_setprio 0
	s_add_i32 s72, 0, 0x18000
	s_add_i32 s73, 0, 0x1c000
	v_add_u32_e32 v166, s72, v152
	v_add_u32_e32 v171, s73, v152
	ds_read_b128 v[154:157], v166
	ds_read_b128 v[158:161], v166 offset:1024
	ds_read_b128 v[162:165], v166 offset:2048
	ds_read_b128 v[166:169], v166 offset:3072
	ds_read_b128 v[172:175], v171
	ds_read_b128 v[176:179], v171 offset:1024
	ds_read_b128 v[180:183], v171 offset:2048
	ds_read_b128 v[184:187], v171 offset:3072
	s_add_u32 s48, s48, 0x40000
	s_addc_u32 s49, s49, 0
	s_mov_b32 m0, s45
	v_lshl_add_u64 v[228:229], s[48:49], 0, v[128:129]
	ds_read_b128 v[188:191], v153 offset:32768
	ds_read_b128 v[192:195], v153 offset:33792
	ds_read_b128 v[196:199], v153 offset:34816
	ds_read_b128 v[200:203], v153 offset:35840
	ds_read_b128 v[204:207], v153 offset:36864
	ds_read_b128 v[208:211], v153 offset:37888
	ds_read_b128 v[212:215], v153 offset:38912
	ds_read_b128 v[216:219], v153 offset:39936
	v_lshl_add_u64 v[228:229], s[48:49], 0, v[130:131]
	s_mov_b32 m0, s50
	s_nop 0
	s_waitcnt vmcnt(0)
	s_waitcnt lgkmcnt(0)
	s_setprio 1
	s_barrier
	v_mfma_f32_16x16x32_bf16 v[122:125], v[154:157], v[188:191], v[122:125]
	v_mfma_f32_16x16x32_bf16 v[118:121], v[162:165], v[188:191], v[118:121]
	v_mfma_f32_16x16x32_bf16 v[114:117], v[154:157], v[196:199], v[114:117]
	v_mfma_f32_16x16x32_bf16 v[98:101], v[162:165], v[196:199], v[98:101]
	v_mfma_f32_16x16x32_bf16 v[134:137], v[154:157], v[204:207], v[134:137]
	v_mfma_f32_16x16x32_bf16 v[102:105], v[162:165], v[204:207], v[102:105]
	v_mfma_f32_16x16x32_bf16 v[110:113], v[154:157], v[212:215], v[110:113]
	v_mfma_f32_16x16x32_bf16 v[86:89], v[162:165], v[212:215], v[86:89]
	v_mfma_f32_16x16x32_bf16 v[122:125], v[158:161], v[192:195], v[122:125]
	v_mfma_f32_16x16x32_bf16 v[118:121], v[166:169], v[192:195], v[118:121]
	v_mfma_f32_16x16x32_bf16 v[114:117], v[158:161], v[200:203], v[114:117]
	v_mfma_f32_16x16x32_bf16 v[98:101], v[166:169], v[200:203], v[98:101]
	v_mfma_f32_16x16x32_bf16 v[134:137], v[158:161], v[208:211], v[134:137]
	v_mfma_f32_16x16x32_bf16 v[102:105], v[166:169], v[208:211], v[102:105]
	v_mfma_f32_16x16x32_bf16 v[110:113], v[158:161], v[216:219], v[110:113]
	v_mfma_f32_16x16x32_bf16 v[86:89], v[166:169], v[216:219], v[86:89]
	v_mfma_f32_16x16x32_bf16 v[106:109], v[172:175], v[188:191], v[106:109]
	v_mfma_f32_16x16x32_bf16 v[94:97], v[180:183], v[188:191], v[94:97]
	v_mfma_f32_16x16x32_bf16 v[90:93], v[172:175], v[196:199], v[90:93]
	v_mfma_f32_16x16x32_bf16 v[82:85], v[180:183], v[196:199], v[82:85]
	v_mfma_f32_16x16x32_bf16 v[78:81], v[172:175], v[204:207], v[78:81]
	v_mfma_f32_16x16x32_bf16 v[74:77], v[180:183], v[204:207], v[74:77]
	v_mfma_f32_16x16x32_bf16 v[70:73], v[172:175], v[212:215], v[70:73]
	v_mfma_f32_16x16x32_bf16 v[66:69], v[180:183], v[212:215], v[66:69]
	v_mfma_f32_16x16x32_bf16 v[106:109], v[176:179], v[192:195], v[106:109]
	v_mfma_f32_16x16x32_bf16 v[94:97], v[184:187], v[192:195], v[94:97]
	v_mfma_f32_16x16x32_bf16 v[90:93], v[176:179], v[200:203], v[90:93]
	v_mfma_f32_16x16x32_bf16 v[82:85], v[184:187], v[200:203], v[82:85]
	v_mfma_f32_16x16x32_bf16 v[78:81], v[176:179], v[208:211], v[78:81]
	v_mfma_f32_16x16x32_bf16 v[74:77], v[184:187], v[208:211], v[74:77]
	v_mfma_f32_16x16x32_bf16 v[70:73], v[176:179], v[216:219], v[70:73]
	v_mfma_f32_16x16x32_bf16 v[66:69], v[184:187], v[216:219], v[66:69]
	s_barrier
	s_setprio 0
	s_add_i32 s48, s72, s33
	v_lshl_add_u64 v[220:221], v[220:221], 0, s[24:25]
	s_mov_b32 m0, s48
	ds_read_b128 v[188:191], v153 offset:49152
	ds_read_b128 v[192:195], v153 offset:50176
	ds_read_b128 v[196:199], v153 offset:51200
	ds_read_b128 v[200:203], v153 offset:52224
	ds_read_b128 v[204:207], v153 offset:53248
	ds_read_b128 v[208:211], v153 offset:54272
	ds_read_b128 v[212:215], v153 offset:55296
	ds_read_b128 v[216:219], v153 offset:56320
	s_add_i32 m0, s48, 0x2000
	s_add_u32 s46, s46, 0x40080
	v_lshl_add_u64 v[220:221], v[222:223], 0, s[24:25]
	s_addc_u32 s47, s47, 0
	s_add_i32 s48, s73, s33
	v_lshl_add_u64 v[220:221], s[46:47], 0, v[126:127]
	s_mov_b32 m0, s48
	s_nop 0
	v_lshl_add_u64 v[220:221], s[46:47], 0, v[132:133]
	s_add_i32 m0, s48, 0x2000
	s_nop 0
	v_lshl_add_u64 v[220:221], v[224:225], 0, s[24:25]
	s_mov_b32 m0, s62
	s_nop 0
	v_lshl_add_u64 v[220:221], v[226:227], 0, s[24:25]
	s_mov_b32 m0, s63
	s_nop 0
	s_waitcnt vmcnt(0)
	s_waitcnt lgkmcnt(0)
	s_setprio 1
	s_barrier
	v_mfma_f32_16x16x32_bf16 v[62:65], v[154:157], v[188:191], v[62:65]
	v_mfma_f32_16x16x32_bf16 v[58:61], v[162:165], v[188:191], v[58:61]
	v_mfma_f32_16x16x32_bf16 v[54:57], v[154:157], v[196:199], v[54:57]
	v_mfma_f32_16x16x32_bf16 v[46:49], v[162:165], v[196:199], v[46:49]
	v_mfma_f32_16x16x32_bf16 v[38:41], v[154:157], v[204:207], v[38:41]
	v_mfma_f32_16x16x32_bf16 v[30:33], v[162:165], v[204:207], v[30:33]
	v_mfma_f32_16x16x32_bf16 v[14:17], v[154:157], v[212:215], v[14:17]
	v_mfma_f32_16x16x32_bf16 v[10:13], v[162:165], v[212:215], v[10:13]
	v_mfma_f32_16x16x32_bf16 v[62:65], v[158:161], v[192:195], v[62:65]
	v_mfma_f32_16x16x32_bf16 v[58:61], v[166:169], v[192:195], v[58:61]
	v_mfma_f32_16x16x32_bf16 v[54:57], v[158:161], v[200:203], v[54:57]
	v_mfma_f32_16x16x32_bf16 v[46:49], v[166:169], v[200:203], v[46:49]
	v_mfma_f32_16x16x32_bf16 v[38:41], v[158:161], v[208:211], v[38:41]
	v_mfma_f32_16x16x32_bf16 v[30:33], v[166:169], v[208:211], v[30:33]
	v_mfma_f32_16x16x32_bf16 v[14:17], v[158:161], v[216:219], v[14:17]
	v_mfma_f32_16x16x32_bf16 v[10:13], v[166:169], v[216:219], v[10:13]
	v_mfma_f32_16x16x32_bf16 v[50:53], v[172:175], v[188:191], v[50:53]
	v_mfma_f32_16x16x32_bf16 v[42:45], v[180:183], v[188:191], v[42:45]
	v_mfma_f32_16x16x32_bf16 v[34:37], v[172:175], v[196:199], v[34:37]
	v_mfma_f32_16x16x32_bf16 v[26:29], v[180:183], v[196:199], v[26:29]
	v_mfma_f32_16x16x32_bf16 v[22:25], v[172:175], v[204:207], v[22:25]
	v_mfma_f32_16x16x32_bf16 v[18:21], v[180:183], v[204:207], v[18:21]
	v_mfma_f32_16x16x32_bf16 v[6:9], v[172:175], v[212:215], v[6:9]
	v_mfma_f32_16x16x32_bf16 v[2:5], v[180:183], v[212:215], v[2:5]
	v_mfma_f32_16x16x32_bf16 v[50:53], v[176:179], v[192:195], v[50:53]
	v_mfma_f32_16x16x32_bf16 v[42:45], v[184:187], v[192:195], v[42:45]
	v_mfma_f32_16x16x32_bf16 v[34:37], v[176:179], v[200:203], v[34:37]
	v_mfma_f32_16x16x32_bf16 v[26:29], v[184:187], v[200:203], v[26:29]
	v_mfma_f32_16x16x32_bf16 v[22:25], v[176:179], v[208:211], v[22:25]
	v_mfma_f32_16x16x32_bf16 v[18:21], v[184:187], v[208:211], v[18:21]
	v_mfma_f32_16x16x32_bf16 v[6:9], v[176:179], v[216:219], v[6:9]
	v_mfma_f32_16x16x32_bf16 v[2:5], v[184:187], v[216:219], v[2:5]
	s_barrier
	s_setprio 0
	s_add_i32 s71, s71, 2
	s_add_u32 s40, s40, 0x100
	s_addc_u32 s41, s41, 0
	s_cmp_gt_u32 s71, 13
; template <class Epi, class Sched, bool ALIGN_EPI = false, bool SP2 = false>
; __device__ __forceinline__ void gemm_phase(PG8_LAS unsigned char* lds, const Gemm g, const Sched& S, const Epi& E) {
;     ...
;         bool keep_ = false;
;         if constexpr (!Epi::AFTER_DRAIN) { if constexpr (Epi::CARRY) keep_ = E.carry(acc, cur, wr, wc, fr, fq); else E(acc, cur, wr, wc, fr, fq); S.done(cur); }
;         if (!has_next) break;
;         if (!keep_) {
; #pragma unroll
;         for (int a = 0; a < 2; ++a)
; #pragma unroll
;             for (int b = 0; b < 2; ++b)
; #pragma unroll
;                 for (int m = 0; m < 4; ++m)
; #pragma unroll
;                     for (int n = 0; n < 2; ++n) acc[a][b][m][n] = (f32x4){0.f, 0.f, 0.f, 0.f};
;         }
;         cur = nxt; cA = nA; cB = nB; ++ui;
.Lpeel_p6_done:
	s_add_u32 s40, s67, 0xffffff00
	s_addc_u32 s41, s68, -1
	s_andn2_b64 vcc, exec, s[6:7]
	s_cbranch_vccnz .LBB0_1079
	v_mov_b32_e32 v2, 0
	s_mov_b32 s18, s28
	s_mov_b32 s10, s30
	s_mov_b64 s[22:23], s[38:39]
	s_mov_b32 s51, s66
	v_mov_b32_e32 v3, v2
	v_mov_b32_e32 v4, v2
	v_mov_b32_e32 v5, v2
	v_mov_b32_e32 v6, v2
	v_mov_b32_e32 v7, v2
	v_mov_b32_e32 v8, v2
	v_mov_b32_e32 v9, v2
	v_mov_b32_e32 v18, v2
	v_mov_b32_e32 v19, v2
	v_mov_b32_e32 v20, v2
	v_mov_b32_e32 v21, v2
	v_mov_b32_e32 v22, v2
	v_mov_b32_e32 v23, v2
	v_mov_b32_e32 v24, v2
	v_mov_b32_e32 v25, v2
	v_mov_b32_e32 v26, v2
	v_mov_b32_e32 v27, v2
	v_mov_b32_e32 v28, v2
	v_mov_b32_e32 v29, v2
	v_mov_b32_e32 v34, v2
	v_mov_b32_e32 v35, v2
	v_mov_b32_e32 v36, v2
	v_mov_b32_e32 v37, v2
	v_mov_b32_e32 v42, v2
	v_mov_b32_e32 v43, v2
	v_mov_b32_e32 v44, v2
	v_mov_b32_e32 v45, v2
	v_mov_b32_e32 v50, v2
	v_mov_b32_e32 v51, v2
	v_mov_b32_e32 v52, v2
	v_mov_b32_e32 v53, v2
	v_mov_b32_e32 v10, v2
	v_mov_b32_e32 v11, v2
	v_mov_b32_e32 v12, v2
	v_mov_b32_e32 v13, v2
	v_mov_b32_e32 v14, v2
	v_mov_b32_e32 v15, v2
	v_mov_b32_e32 v16, v2
	v_mov_b32_e32 v17, v2
	v_mov_b32_e32 v30, v2
	v_mov_b32_e32 v31, v2
	v_mov_b32_e32 v32, v2
	v_mov_b32_e32 v33, v2
	v_mov_b32_e32 v38, v2
	v_mov_b32_e32 v39, v2
	v_mov_b32_e32 v40, v2
	v_mov_b32_e32 v41, v2
	v_mov_b32_e32 v46, v2
	v_mov_b32_e32 v47, v2
	v_mov_b32_e32 v48, v2
	v_mov_b32_e32 v49, v2
	v_mov_b32_e32 v54, v2
	v_mov_b32_e32 v55, v2
	v_mov_b32_e32 v56, v2
	v_mov_b32_e32 v57, v2
	v_mov_b32_e32 v58, v2
	v_mov_b32_e32 v59, v2
	v_mov_b32_e32 v60, v2
	v_mov_b32_e32 v61, v2
	v_mov_b32_e32 v62, v2
	v_mov_b32_e32 v63, v2
	v_mov_b32_e32 v64, v2
	v_mov_b32_e32 v65, v2
	v_mov_b32_e32 v66, v2
	v_mov_b32_e32 v67, v2
	v_mov_b32_e32 v68, v2
	v_mov_b32_e32 v69, v2
	v_mov_b32_e32 v70, v2
	v_mov_b32_e32 v71, v2
	v_mov_b32_e32 v72, v2
	v_mov_b32_e32 v73, v2
	v_mov_b32_e32 v74, v2
	v_mov_b32_e32 v75, v2
	v_mov_b32_e32 v76, v2
	v_mov_b32_e32 v77, v2
	v_mov_b32_e32 v78, v2
	v_mov_b32_e32 v79, v2
	v_mov_b32_e32 v80, v2
	v_mov_b32_e32 v81, v2
	v_mov_b32_e32 v82, v2
	v_mov_b32_e32 v83, v2
	v_mov_b32_e32 v84, v2
	v_mov_b32_e32 v85, v2
	v_mov_b32_e32 v90, v2
	v_mov_b32_e32 v91, v2
	v_mov_b32_e32 v92, v2
	v_mov_b32_e32 v93, v2
	v_mov_b32_e32 v94, v2
	v_mov_b32_e32 v95, v2
	v_mov_b32_e32 v96, v2
	v_mov_b32_e32 v97, v2
	v_mov_b32_e32 v106, v2
	v_mov_b32_e32 v107, v2
	v_mov_b32_e32 v108, v2
	v_mov_b32_e32 v109, v2
	v_mov_b32_e32 v86, v2
	v_mov_b32_e32 v87, v2
	v_mov_b32_e32 v88, v2
	v_mov_b32_e32 v89, v2
	v_mov_b32_e32 v110, v2
	v_mov_b32_e32 v111, v2
	v_mov_b32_e32 v112, v2
	v_mov_b32_e32 v113, v2
	v_mov_b32_e32 v102, v2
	v_mov_b32_e32 v103, v2
	v_mov_b32_e32 v104, v2
	v_mov_b32_e32 v105, v2
	v_mov_b32_e32 v134, v2
	v_mov_b32_e32 v135, v2
	v_mov_b32_e32 v136, v2
	v_mov_b32_e32 v137, v2
	v_mov_b32_e32 v98, v2
	v_mov_b32_e32 v99, v2
	v_mov_b32_e32 v100, v2
	v_mov_b32_e32 v101, v2
	v_mov_b32_e32 v114, v2
	v_mov_b32_e32 v115, v2
	v_mov_b32_e32 v116, v2
	v_mov_b32_e32 v117, v2
	v_mov_b32_e32 v118, v2
	v_mov_b32_e32 v119, v2
	v_mov_b32_e32 v120, v2
	v_mov_b32_e32 v121, v2
	v_mov_b32_e32 v122, v2
	v_mov_b32_e32 v123, v2
	v_mov_b32_e32 v124, v2
	v_mov_b32_e32 v125, v2
	s_andn2_b64 vcc, exec, s[0:1]
	s_cbranch_vccnz .LBB0_1080

; #define PG8_STAGE(bufoff, gbase, voff) do { _Pragma("unroll") for (int _i = 0; _i < 2; ++_i) \
;         __builtin_amdgcn_global_load_lds((const unsigned*)((const char*)(gbase) + (voff)[_i]), (PG8_LAS unsigned*)(lds + (bufoff) + ldsw + _i * 8192), 16, 0, 0); } while (0)
; #define PG8_LDA(dst, b, h) do { _Pragma("unroll") for (int m = 0; m < 4; ++m) _Pragma("unroll") for (int k = 0; k < 2; ++k) dst[m][k] = *(const PG8_LAS bf16x8*)(lds + PG8_SA(b, h) + aoff + m * 2048 + k * 1024); } while (0)
; #define PG8_LDB(dst, b, h) do { _Pragma("unroll") for (int n = 0; n < 2; ++n) _Pragma("unroll") for (int k = 0; k < 2; ++k) dst[n][k] = *(const PG8_LAS bf16x8*)(lds + PG8_SB(b, h) + boff + n * 2048 + k * 1024); } while (0)
; #define PG8_MMA(ai, bj, At, Bt) do { __builtin_amdgcn_s_setprio(1); _Pragma("unroll") for (int m = 0; m < 4; ++m) _Pragma("unroll") for (int n = 0; n < 2; ++n) _Pragma("unroll") for (int k = 0; k < 2; ++k) \
;         acc[ai][bj][m][n] = __builtin_amdgcn_mfma_f32_16x16x32_bf16(Bt[n][k], At[m][k], acc[ai][bj][m][n], 0, 0, 0); __builtin_amdgcn_s_setprio(0); } while (0)
; #define PG8_WAIT_V(n) asm volatile("s_waitcnt vmcnt(" #n ")" ::: "memory")
; #define PG8_WAIT_L(n) asm volatile("s_waitcnt lgkmcnt(" #n ")" ::: "memory")
; #define PG8_BAR __builtin_amdgcn_s_barrier()
; #define PG8_SCHED __builtin_amdgcn_sched_barrier(0)
; template <class Epi, class Sched, bool ALIGN_EPI = false, bool SP2 = false>
; __device__ __forceinline__ void gemm_phase(PG8_LAS unsigned char* lds, const Gemm g, const Sched& S, const Epi& E) {
;     ...
;             PG8_LDB(B0, 0, 0); PG8_LDB(B1, 0, 1); PG8_SCHED; PG8_LDA(At, 0, 0); PG8_STAGE(PG8_SA(1, 1), a1 + hstepA, voffA);
;             PG8_WAIT_V(8); PG8_WAIT_L(0); PG8_BAR; PG8_MMA(0, 0, At, B0); PG8_MMA(0, 1, At, B1); PG8_BAR; PG8_SCHED;
;             PG8_LDA(At, 0, 1); PG8_STAGE(PG8_SB(0, 0), b2, voffB); PG8_STAGE(PG8_SB(0, 1), b2 + hstepB, voffB); PG8_STAGE(PG8_SA(0, 0), a2, voffA);
;             PG8_WAIT_V(8); PG8_WAIT_L(0); PG8_BAR; PG8_MMA(1, 0, At, B0); PG8_MMA(1, 1, At, B1); PG8_BAR; PG8_SCHED;
.LBB0_1339:
	v_add_u32_e32 v153, s56, v151
	ds_read_b128 v[154:157], v153
	ds_read_b128 v[158:161], v153 offset:1024
	ds_read_b128 v[162:165], v153 offset:2048
	ds_read_b128 v[166:169], v153 offset:3072
	v_add_u32_e32 v153, s57, v151
	ds_read_b128 v[172:175], v153
	ds_read_b128 v[176:179], v153 offset:1024
	ds_read_b128 v[180:183], v153 offset:2048
	ds_read_b128 v[184:187], v153 offset:3072
	s_add_u32 s38, s14, s36
	s_addc_u32 s39, s15, s37
	s_cmp_eq_u32 s65, 60
	s_cselect_b32 s42, s59, s38
	s_cselect_b32 s43, s25, s39
	s_cselect_b32 s40, s62, s63
	s_cselect_b32 s41, s23, s64
	s_add_u32 s38, s42, 0x8000
	s_addc_u32 s39, s43, 0
	v_lshl_add_u64 v[220:221], s[14:15], 0, v[148:149]
	s_add_i32 m0, s45, 0xc000
	ds_read_b128 v[188:191], v152
	ds_read_b128 v[192:195], v152 offset:1024
	ds_read_b128 v[196:199], v152 offset:2048
	ds_read_b128 v[200:203], v152 offset:3072
	ds_read_b128 v[204:207], v152 offset:4096
	ds_read_b128 v[208:211], v152 offset:5120
	ds_read_b128 v[212:215], v152 offset:6144
	ds_read_b128 v[216:219], v152 offset:7168
	global_load_lds_dwordx4 v[220:221], off
	v_lshl_add_u64 v[220:221], s[14:15], 0, v[146:147]
	s_add_i32 m0, s45, 0xe000
	s_nop 0
	global_load_lds_dwordx4 v[220:221], off
	s_waitcnt vmcnt(8)
	s_waitcnt lgkmcnt(0)
	s_setprio 1
	s_barrier
	v_mfma_f32_16x16x32_bf16 v[122:125], v[154:157], v[188:191], v[122:125]
	v_mfma_f32_16x16x32_bf16 v[126:129], v[162:165], v[188:191], v[126:129]
	v_mfma_f32_16x16x32_bf16 v[118:121], v[154:157], v[196:199], v[118:121]
	v_mfma_f32_16x16x32_bf16 v[106:109], v[162:165], v[196:199], v[106:109]
	v_mfma_f32_16x16x32_bf16 v[98:101], v[154:157], v[204:207], v[98:101]
	v_mfma_f32_16x16x32_bf16 v[90:93], v[162:165], v[204:207], v[90:93]
	v_mfma_f32_16x16x32_bf16 v[110:113], v[154:157], v[212:215], v[110:113]
	v_mfma_f32_16x16x32_bf16 v[82:85], v[162:165], v[212:215], v[82:85]
	v_mfma_f32_16x16x32_bf16 v[122:125], v[158:161], v[192:195], v[122:125]
	v_mfma_f32_16x16x32_bf16 v[126:129], v[166:169], v[192:195], v[126:129]
	v_mfma_f32_16x16x32_bf16 v[118:121], v[158:161], v[200:203], v[118:121]
	v_mfma_f32_16x16x32_bf16 v[106:109], v[166:169], v[200:203], v[106:109]
	v_mfma_f32_16x16x32_bf16 v[98:101], v[158:161], v[208:211], v[98:101]
	v_mfma_f32_16x16x32_bf16 v[90:93], v[166:169], v[208:211], v[90:93]
	v_mfma_f32_16x16x32_bf16 v[110:113], v[158:161], v[216:219], v[110:113]
	v_mfma_f32_16x16x32_bf16 v[82:85], v[166:169], v[216:219], v[82:85]
	v_mfma_f32_16x16x32_bf16 v[114:117], v[172:175], v[188:191], v[114:117]
	v_mfma_f32_16x16x32_bf16 v[102:105], v[180:183], v[188:191], v[102:105]
	v_mfma_f32_16x16x32_bf16 v[94:97], v[172:175], v[196:199], v[94:97]
	v_mfma_f32_16x16x32_bf16 v[86:89], v[180:183], v[196:199], v[86:89]
	v_mfma_f32_16x16x32_bf16 v[78:81], v[172:175], v[204:207], v[78:81]
	v_mfma_f32_16x16x32_bf16 v[70:73], v[180:183], v[204:207], v[70:73]
	v_mfma_f32_16x16x32_bf16 v[66:69], v[172:175], v[212:215], v[66:69]
	v_mfma_f32_16x16x32_bf16 v[74:77], v[180:183], v[212:215], v[74:77]
	v_mfma_f32_16x16x32_bf16 v[114:117], v[176:179], v[192:195], v[114:117]
	v_mfma_f32_16x16x32_bf16 v[102:105], v[184:187], v[192:195], v[102:105]
	v_mfma_f32_16x16x32_bf16 v[94:97], v[176:179], v[200:203], v[94:97]
	v_mfma_f32_16x16x32_bf16 v[86:89], v[184:187], v[200:203], v[86:89]
	v_mfma_f32_16x16x32_bf16 v[78:81], v[176:179], v[208:211], v[78:81]
	v_mfma_f32_16x16x32_bf16 v[70:73], v[184:187], v[208:211], v[70:73]
	v_mfma_f32_16x16x32_bf16 v[66:69], v[176:179], v[216:219], v[66:69]
	v_mfma_f32_16x16x32_bf16 v[74:77], v[184:187], v[216:219], v[74:77]
	s_barrier
	s_setprio 0
	s_add_i32 s66, s56, s44
	v_lshl_add_u64 v[220:221], s[40:41], 0, v[132:133]
	s_mov_b32 m0, s66
	ds_read_b128 v[188:191], v152 offset:16384
	ds_read_b128 v[192:195], v152 offset:17408
	ds_read_b128 v[196:199], v152 offset:18432
	ds_read_b128 v[200:203], v152 offset:19456
	ds_read_b128 v[204:207], v152 offset:20480
	ds_read_b128 v[208:211], v152 offset:21504
	ds_read_b128 v[212:215], v152 offset:22528
	ds_read_b128 v[216:219], v152 offset:23552
	global_load_lds_dwordx4 v[220:221], off
	s_add_i32 m0, s66, 0x2000
	s_add_u32 s66, s40, 0x100000
	v_lshl_add_u64 v[222:223], s[40:41], 0, v[136:137]
	s_addc_u32 s67, s41, 0
	s_add_i32 s68, s57, s44
	global_load_lds_dwordx4 v[222:223], off
	v_lshl_add_u64 v[224:225], s[66:67], 0, v[132:133]
	s_mov_b32 m0, s68
	s_nop 0
	global_load_lds_dwordx4 v[224:225], off
	v_lshl_add_u64 v[224:225], s[66:67], 0, v[136:137]
	s_add_i32 m0, s68, 0x2000
	s_nop 0
	global_load_lds_dwordx4 v[224:225], off
	v_lshl_add_u64 v[224:225], s[42:43], 0, v[130:131]
	s_mov_b32 m0, s45
	s_nop 0
	global_load_lds_dwordx4 v[224:225], off
	v_lshl_add_u64 v[224:225], s[42:43], 0, v[134:135]
	s_mov_b32 m0, s46
	s_nop 0
	global_load_lds_dwordx4 v[224:225], off
	s_waitcnt vmcnt(8)
	s_waitcnt lgkmcnt(0)
	s_setprio 1
	s_barrier
; #define PG8_STAGE(bufoff, gbase, voff) do { _Pragma("unroll") for (int _i = 0; _i < 2; ++_i) \
;         __builtin_amdgcn_global_load_lds((const unsigned*)((const char*)(gbase) + (voff)[_i]), (PG8_LAS unsigned*)(lds + (bufoff) + ldsw + _i * 8192), 16, 0, 0); } while (0)
; #define PG8_LDA(dst, b, h) do { _Pragma("unroll") for (int m = 0; m < 4; ++m) _Pragma("unroll") for (int k = 0; k < 2; ++k) dst[m][k] = *(const PG8_LAS bf16x8*)(lds + PG8_SA(b, h) + aoff + m * 2048 + k * 1024); } while (0)
; #define PG8_LDB(dst, b, h) do { _Pragma("unroll") for (int n = 0; n < 2; ++n) _Pragma("unroll") for (int k = 0; k < 2; ++k) dst[n][k] = *(const PG8_LAS bf16x8*)(lds + PG8_SB(b, h) + boff + n * 2048 + k * 1024); } while (0)
; #define PG8_MMA(ai, bj, At, Bt) do { __builtin_amdgcn_s_setprio(1); _Pragma("unroll") for (int m = 0; m < 4; ++m) _Pragma("unroll") for (int n = 0; n < 2; ++n) _Pragma("unroll") for (int k = 0; k < 2; ++k) \
;         acc[ai][bj][m][n] = __builtin_amdgcn_mfma_f32_16x16x32_bf16(Bt[n][k], At[m][k], acc[ai][bj][m][n], 0, 0, 0); __builtin_amdgcn_s_setprio(0); } while (0)
; #define PG8_WAIT_V(n) asm volatile("s_waitcnt vmcnt(" #n ")" ::: "memory")
; #define PG8_WAIT_L(n) asm volatile("s_waitcnt lgkmcnt(" #n ")" ::: "memory")
; #define PG8_BAR __builtin_amdgcn_s_barrier()
; #define PG8_SCHED __builtin_amdgcn_sched_barrier(0)
; template <class Epi, class Sched, bool ALIGN_EPI = false, bool SP2 = false>
; __device__ __forceinline__ void gemm_phase(PG8_LAS unsigned char* lds, const Gemm g, const Sched& S, const Epi& E) {
;     ...
;             PG8_WAIT_V(8); PG8_WAIT_L(0); PG8_BAR; PG8_MMA(1, 0, At, B0); PG8_MMA(1, 1, At, B1); PG8_BAR; PG8_SCHED;
;             PG8_LDB(B0, 1, 0); PG8_LDB(B1, 1, 1); PG8_SCHED; PG8_LDA(At, 1, 0); PG8_STAGE(PG8_SA(0, 1), a2 + hstepA, voffA);
;             PG8_WAIT_V(8); PG8_WAIT_L(0); PG8_BAR; PG8_MMA(0, 0, At, B0); PG8_MMA(0, 1, At, B1); PG8_BAR; PG8_SCHED;
	v_mfma_f32_16x16x32_bf16 v[62:65], v[154:157], v[188:191], v[62:65]
	v_mfma_f32_16x16x32_bf16 v[58:61], v[162:165], v[188:191], v[58:61]
	v_mfma_f32_16x16x32_bf16 v[54:57], v[154:157], v[196:199], v[54:57]
	v_mfma_f32_16x16x32_bf16 v[46:49], v[162:165], v[196:199], v[46:49]
	v_mfma_f32_16x16x32_bf16 v[38:41], v[154:157], v[204:207], v[38:41]
	v_mfma_f32_16x16x32_bf16 v[30:33], v[162:165], v[204:207], v[30:33]
	v_mfma_f32_16x16x32_bf16 v[14:17], v[154:157], v[212:215], v[14:17]
	v_mfma_f32_16x16x32_bf16 v[10:13], v[162:165], v[212:215], v[10:13]
	v_mfma_f32_16x16x32_bf16 v[62:65], v[158:161], v[192:195], v[62:65]
	v_mfma_f32_16x16x32_bf16 v[58:61], v[166:169], v[192:195], v[58:61]
	v_mfma_f32_16x16x32_bf16 v[54:57], v[158:161], v[200:203], v[54:57]
	v_mfma_f32_16x16x32_bf16 v[46:49], v[166:169], v[200:203], v[46:49]
	v_mfma_f32_16x16x32_bf16 v[38:41], v[158:161], v[208:211], v[38:41]
	v_mfma_f32_16x16x32_bf16 v[30:33], v[166:169], v[208:211], v[30:33]
	v_mfma_f32_16x16x32_bf16 v[14:17], v[158:161], v[216:219], v[14:17]
	v_mfma_f32_16x16x32_bf16 v[10:13], v[166:169], v[216:219], v[10:13]
	v_mfma_f32_16x16x32_bf16 v[50:53], v[172:175], v[188:191], v[50:53]
	v_mfma_f32_16x16x32_bf16 v[42:45], v[180:183], v[188:191], v[42:45]
	v_mfma_f32_16x16x32_bf16 v[34:37], v[172:175], v[196:199], v[34:37]
	v_mfma_f32_16x16x32_bf16 v[26:29], v[180:183], v[196:199], v[26:29]
	v_mfma_f32_16x16x32_bf16 v[22:25], v[172:175], v[204:207], v[22:25]
	v_mfma_f32_16x16x32_bf16 v[18:21], v[180:183], v[204:207], v[18:21]
	v_mfma_f32_16x16x32_bf16 v[6:9], v[172:175], v[212:215], v[6:9]
	v_mfma_f32_16x16x32_bf16 v[2:5], v[180:183], v[212:215], v[2:5]
	v_mfma_f32_16x16x32_bf16 v[50:53], v[176:179], v[192:195], v[50:53]
	v_mfma_f32_16x16x32_bf16 v[42:45], v[184:187], v[192:195], v[42:45]
	v_mfma_f32_16x16x32_bf16 v[34:37], v[176:179], v[200:203], v[34:37]
	v_mfma_f32_16x16x32_bf16 v[26:29], v[184:187], v[200:203], v[26:29]
	v_mfma_f32_16x16x32_bf16 v[22:25], v[176:179], v[208:211], v[22:25]
	v_mfma_f32_16x16x32_bf16 v[18:21], v[184:187], v[208:211], v[18:21]
	v_mfma_f32_16x16x32_bf16 v[6:9], v[176:179], v[216:219], v[6:9]
	v_mfma_f32_16x16x32_bf16 v[2:5], v[184:187], v[216:219], v[2:5]
	s_barrier
	s_setprio 0
	s_add_i32 s66, 0, 0x18000
	v_add_u32_e32 v153, s66, v151
	s_add_i32 s67, 0, 0x1c000
	ds_read_b128 v[154:157], v153
	ds_read_b128 v[158:161], v153 offset:1024
	ds_read_b128 v[162:165], v153 offset:2048
	ds_read_b128 v[166:169], v153 offset:3072
	v_add_u32_e32 v153, s67, v151
	ds_read_b128 v[172:175], v153
	ds_read_b128 v[176:179], v153 offset:1024
	ds_read_b128 v[180:183], v153 offset:2048
	ds_read_b128 v[184:187], v153 offset:3072
	s_add_u32 s42, s42, 0x4000
	s_addc_u32 s43, s43, 0
	s_mov_b32 m0, s47
	v_lshl_add_u64 v[224:225], s[42:43], 0, v[130:131]
	ds_read_b128 v[188:191], v152 offset:32768
	ds_read_b128 v[192:195], v152 offset:33792
	ds_read_b128 v[196:199], v152 offset:34816
	ds_read_b128 v[200:203], v152 offset:35840
	ds_read_b128 v[204:207], v152 offset:36864
	ds_read_b128 v[208:211], v152 offset:37888
	ds_read_b128 v[212:215], v152 offset:38912
	ds_read_b128 v[216:219], v152 offset:39936
	global_load_lds_dwordx4 v[224:225], off
	v_lshl_add_u64 v[224:225], s[42:43], 0, v[134:135]
	s_mov_b32 m0, s48
	s_nop 0
	global_load_lds_dwordx4 v[224:225], off
	s_waitcnt vmcnt(8)
	s_waitcnt lgkmcnt(0)
	s_setprio 1
	s_barrier
	v_mfma_f32_16x16x32_bf16 v[122:125], v[154:157], v[188:191], v[122:125]
	v_mfma_f32_16x16x32_bf16 v[126:129], v[162:165], v[188:191], v[126:129]
	v_mfma_f32_16x16x32_bf16 v[118:121], v[154:157], v[196:199], v[118:121]
	v_mfma_f32_16x16x32_bf16 v[106:109], v[162:165], v[196:199], v[106:109]
	v_mfma_f32_16x16x32_bf16 v[98:101], v[154:157], v[204:207], v[98:101]
	v_mfma_f32_16x16x32_bf16 v[90:93], v[162:165], v[204:207], v[90:93]
	v_mfma_f32_16x16x32_bf16 v[110:113], v[154:157], v[212:215], v[110:113]
	v_mfma_f32_16x16x32_bf16 v[82:85], v[162:165], v[212:215], v[82:85]
	v_mfma_f32_16x16x32_bf16 v[122:125], v[158:161], v[192:195], v[122:125]
	v_mfma_f32_16x16x32_bf16 v[126:129], v[166:169], v[192:195], v[126:129]
	v_mfma_f32_16x16x32_bf16 v[118:121], v[158:161], v[200:203], v[118:121]
	v_mfma_f32_16x16x32_bf16 v[106:109], v[166:169], v[200:203], v[106:109]
	v_mfma_f32_16x16x32_bf16 v[98:101], v[158:161], v[208:211], v[98:101]
	v_mfma_f32_16x16x32_bf16 v[90:93], v[166:169], v[208:211], v[90:93]
	v_mfma_f32_16x16x32_bf16 v[110:113], v[158:161], v[216:219], v[110:113]
	v_mfma_f32_16x16x32_bf16 v[82:85], v[166:169], v[216:219], v[82:85]
	v_mfma_f32_16x16x32_bf16 v[114:117], v[172:175], v[188:191], v[114:117]
	v_mfma_f32_16x16x32_bf16 v[102:105], v[180:183], v[188:191], v[102:105]
	v_mfma_f32_16x16x32_bf16 v[94:97], v[172:175], v[196:199], v[94:97]
	v_mfma_f32_16x16x32_bf16 v[86:89], v[180:183], v[196:199], v[86:89]
	v_mfma_f32_16x16x32_bf16 v[78:81], v[172:175], v[204:207], v[78:81]
	v_mfma_f32_16x16x32_bf16 v[70:73], v[180:183], v[204:207], v[70:73]
	v_mfma_f32_16x16x32_bf16 v[66:69], v[172:175], v[212:215], v[66:69]
	v_mfma_f32_16x16x32_bf16 v[74:77], v[180:183], v[212:215], v[74:77]
	v_mfma_f32_16x16x32_bf16 v[114:117], v[176:179], v[192:195], v[114:117]
	v_mfma_f32_16x16x32_bf16 v[102:105], v[184:187], v[192:195], v[102:105]
	v_mfma_f32_16x16x32_bf16 v[94:97], v[176:179], v[200:203], v[94:97]
	v_mfma_f32_16x16x32_bf16 v[86:89], v[184:187], v[200:203], v[86:89]
	v_mfma_f32_16x16x32_bf16 v[78:81], v[176:179], v[208:211], v[78:81]
	v_mfma_f32_16x16x32_bf16 v[70:73], v[184:187], v[208:211], v[70:73]
	v_mfma_f32_16x16x32_bf16 v[66:69], v[176:179], v[216:219], v[66:69]
	v_mfma_f32_16x16x32_bf16 v[74:77], v[184:187], v[216:219], v[74:77]
	s_barrier
; #define PG8_STAGE(bufoff, gbase, voff) do { _Pragma("unroll") for (int _i = 0; _i < 2; ++_i) \
;         __builtin_amdgcn_global_load_lds((const unsigned*)((const char*)(gbase) + (voff)[_i]), (PG8_LAS unsigned*)(lds + (bufoff) + ldsw + _i * 8192), 16, 0, 0); } while (0)
; #define PG8_LDA(dst, b, h) do { _Pragma("unroll") for (int m = 0; m < 4; ++m) _Pragma("unroll") for (int k = 0; k < 2; ++k) dst[m][k] = *(const PG8_LAS bf16x8*)(lds + PG8_SA(b, h) + aoff + m * 2048 + k * 1024); } while (0)
; #define PG8_MMA(ai, bj, At, Bt) do { __builtin_amdgcn_s_setprio(1); _Pragma("unroll") for (int m = 0; m < 4; ++m) _Pragma("unroll") for (int n = 0; n < 2; ++n) _Pragma("unroll") for (int k = 0; k < 2; ++k) \
;         acc[ai][bj][m][n] = __builtin_amdgcn_mfma_f32_16x16x32_bf16(Bt[n][k], At[m][k], acc[ai][bj][m][n], 0, 0, 0); __builtin_amdgcn_s_setprio(0); } while (0)
; #define PG8_WAIT_V(n) asm volatile("s_waitcnt vmcnt(" #n ")" ::: "memory")
; #define PG8_WAIT_L(n) asm volatile("s_waitcnt lgkmcnt(" #n ")" ::: "memory")
; #define PG8_BAR __builtin_amdgcn_s_barrier()
; #define PG8_SCHED __builtin_amdgcn_sched_barrier(0)
; template <class Epi, class Sched, bool ALIGN_EPI = false, bool SP2 = false>
; __device__ __forceinline__ void gemm_phase(PG8_LAS unsigned char* lds, const Gemm g, const Sched& S, const Epi& E) {
;     ...
;         for (int t = 0; t < nt; t += 2) {
;             const bool last = (t == nt - 2);
;             const char* a1 = cA + (size_t)(t + 1) * kstepA;
;             const char* a2 = last ? nA : cA + (size_t)(t + 2) * kstepA; const char* b2 = last ? nB : cB + (size_t)(t + 2) * kstep;
;     ...
;             PG8_LDA(At, 1, 1); PG8_STAGE(PG8_SB(1, 0), b3, voffB); PG8_STAGE(PG8_SB(1, 1), b3 + hstepB, voffB); PG8_STAGE(PG8_SA(1, 0), a3, voffA);
;             PG8_WAIT_V(8); PG8_WAIT_L(0); PG8_BAR; PG8_MMA(1, 0, At, B0); PG8_MMA(1, 1, At, B1); PG8_BAR; PG8_SCHED;
	s_setprio 0
	s_add_i32 s42, s66, s44
	v_lshl_add_u64 v[220:221], v[220:221], 0, s[16:17]
	s_mov_b32 m0, s42
	ds_read_b128 v[188:191], v152 offset:49152
	ds_read_b128 v[192:195], v152 offset:50176
	ds_read_b128 v[196:199], v152 offset:51200
	ds_read_b128 v[200:203], v152 offset:52224
	ds_read_b128 v[204:207], v152 offset:53248
	ds_read_b128 v[208:211], v152 offset:54272
	ds_read_b128 v[212:215], v152 offset:55296
	ds_read_b128 v[216:219], v152 offset:56320
	global_load_lds_dwordx4 v[220:221], off
	s_add_i32 m0, s42, 0x2000
	s_add_u32 s40, s40, 0x100080
	v_lshl_add_u64 v[220:221], v[222:223], 0, s[16:17]
	s_addc_u32 s41, s41, 0
	s_add_i32 s42, s67, s44
	global_load_lds_dwordx4 v[220:221], off
	v_lshl_add_u64 v[220:221], s[40:41], 0, v[132:133]
	s_mov_b32 m0, s42
	s_nop 0
	global_load_lds_dwordx4 v[220:221], off
	v_lshl_add_u64 v[220:221], s[40:41], 0, v[136:137]
	s_add_i32 m0, s42, 0x2000
	s_nop 0
	global_load_lds_dwordx4 v[220:221], off
	v_lshl_add_u64 v[220:221], s[38:39], 0, v[130:131]
	s_mov_b32 m0, s50
	s_nop 0
	global_load_lds_dwordx4 v[220:221], off
	v_lshl_add_u64 v[220:221], s[38:39], 0, v[134:135]
	s_mov_b32 m0, s51
	s_nop 0
	global_load_lds_dwordx4 v[220:221], off
	s_waitcnt vmcnt(8)
	s_waitcnt lgkmcnt(0)
	s_setprio 1
	s_barrier
	v_mfma_f32_16x16x32_bf16 v[62:65], v[154:157], v[188:191], v[62:65]
	v_mfma_f32_16x16x32_bf16 v[58:61], v[162:165], v[188:191], v[58:61]
	v_mfma_f32_16x16x32_bf16 v[54:57], v[154:157], v[196:199], v[54:57]
	v_mfma_f32_16x16x32_bf16 v[46:49], v[162:165], v[196:199], v[46:49]
	v_mfma_f32_16x16x32_bf16 v[38:41], v[154:157], v[204:207], v[38:41]
	v_mfma_f32_16x16x32_bf16 v[30:33], v[162:165], v[204:207], v[30:33]
	v_mfma_f32_16x16x32_bf16 v[14:17], v[154:157], v[212:215], v[14:17]
	v_mfma_f32_16x16x32_bf16 v[10:13], v[162:165], v[212:215], v[10:13]
	v_mfma_f32_16x16x32_bf16 v[62:65], v[158:161], v[192:195], v[62:65]
	v_mfma_f32_16x16x32_bf16 v[58:61], v[166:169], v[192:195], v[58:61]
	v_mfma_f32_16x16x32_bf16 v[54:57], v[158:161], v[200:203], v[54:57]
	v_mfma_f32_16x16x32_bf16 v[46:49], v[166:169], v[200:203], v[46:49]
	v_mfma_f32_16x16x32_bf16 v[38:41], v[158:161], v[208:211], v[38:41]
	v_mfma_f32_16x16x32_bf16 v[30:33], v[166:169], v[208:211], v[30:33]
	v_mfma_f32_16x16x32_bf16 v[14:17], v[158:161], v[216:219], v[14:17]
	v_mfma_f32_16x16x32_bf16 v[10:13], v[166:169], v[216:219], v[10:13]
	v_mfma_f32_16x16x32_bf16 v[50:53], v[172:175], v[188:191], v[50:53]
	v_mfma_f32_16x16x32_bf16 v[42:45], v[180:183], v[188:191], v[42:45]
	v_mfma_f32_16x16x32_bf16 v[34:37], v[172:175], v[196:199], v[34:37]
	v_mfma_f32_16x16x32_bf16 v[26:29], v[180:183], v[196:199], v[26:29]
	v_mfma_f32_16x16x32_bf16 v[22:25], v[172:175], v[204:207], v[22:25]
	v_mfma_f32_16x16x32_bf16 v[18:21], v[180:183], v[204:207], v[18:21]
	v_mfma_f32_16x16x32_bf16 v[6:9], v[172:175], v[212:215], v[6:9]
	v_mfma_f32_16x16x32_bf16 v[2:5], v[180:183], v[212:215], v[2:5]
	v_mfma_f32_16x16x32_bf16 v[50:53], v[176:179], v[192:195], v[50:53]
	v_mfma_f32_16x16x32_bf16 v[42:45], v[184:187], v[192:195], v[42:45]
	v_mfma_f32_16x16x32_bf16 v[34:37], v[176:179], v[200:203], v[34:37]
	v_mfma_f32_16x16x32_bf16 v[26:29], v[184:187], v[200:203], v[26:29]
	v_mfma_f32_16x16x32_bf16 v[22:25], v[176:179], v[208:211], v[22:25]
	v_mfma_f32_16x16x32_bf16 v[18:21], v[184:187], v[208:211], v[18:21]
	v_mfma_f32_16x16x32_bf16 v[6:9], v[176:179], v[216:219], v[6:9]
	v_mfma_f32_16x16x32_bf16 v[2:5], v[184:187], v[216:219], v[2:5]
	s_barrier
	s_setprio 0
	s_add_i32 s65, s65, 2
	s_add_u32 s63, s63, 0x100
	s_addc_u32 s64, s64, 0
	s_add_u32 s36, s36, 0x10000
	s_addc_u32 s37, s37, 0
	v_lshl_add_u64 v[148:149], v[148:149], 0, s[18:19]
	s_cmp_gt_u32 s65, 59
	v_lshl_add_u64 v[146:147], v[146:147], 0, s[18:19]
	s_cbranch_scc0 .LBB0_1339
	s_cmp_gt_u32 s65, 61
	s_cbranch_scc1 .Lpeel_p8_done
	s_and_b64 vcc, exec, s[4:5]
	s_cbranch_vccnz .LBB0_1339
	v_add_u32_e32 v153, s56, v151
	ds_read_b128 v[154:157], v153
	ds_read_b128 v[158:161], v153 offset:1024
	ds_read_b128 v[162:165], v153 offset:2048
	ds_read_b128 v[166:169], v153 offset:3072
	v_add_u32_e32 v153, s57, v151
	ds_read_b128 v[172:175], v153
	ds_read_b128 v[176:179], v153 offset:1024
	ds_read_b128 v[180:183], v153 offset:2048
	ds_read_b128 v[184:187], v153 offset:3072
	s_add_u32 s38, s14, s36
	s_addc_u32 s39, s15, s37
	s_cmp_eq_u32 s65, 60
	s_cselect_b32 s42, s59, s38
	s_cselect_b32 s43, s25, s39
	s_cselect_b32 s40, s62, s63
	s_cselect_b32 s41, s23, s64
	s_add_u32 s38, s42, 0x8000
	s_addc_u32 s39, s43, 0
	v_lshl_add_u64 v[220:221], s[14:15], 0, v[148:149]
	s_add_i32 m0, s45, 0xc000
	ds_read_b128 v[188:191], v152
	ds_read_b128 v[192:195], v152 offset:1024
	ds_read_b128 v[196:199], v152 offset:2048
	ds_read_b128 v[200:203], v152 offset:3072
	ds_read_b128 v[204:207], v152 offset:4096
	ds_read_b128 v[208:211], v152 offset:5120
	ds_read_b128 v[212:215], v152 offset:6144
	ds_read_b128 v[216:219], v152 offset:7168
	global_load_lds_dwordx4 v[220:221], off
	v_lshl_add_u64 v[220:221], s[14:15], 0, v[146:147]
	s_add_i32 m0, s45, 0xe000
	s_nop 0
	global_load_lds_dwordx4 v[220:221], off
	s_waitcnt vmcnt(8)
	s_waitcnt lgkmcnt(0)
	s_setprio 1
	s_barrier
; #define PG8_STAGE(bufoff, gbase, voff) do { _Pragma("unroll") for (int _i = 0; _i < 2; ++_i) \
;         __builtin_amdgcn_global_load_lds((const unsigned*)((const char*)(gbase) + (voff)[_i]), (PG8_LAS unsigned*)(lds + (bufoff) + ldsw + _i * 8192), 16, 0, 0); } while (0)
; #define PG8_LDA(dst, b, h) do { _Pragma("unroll") for (int m = 0; m < 4; ++m) _Pragma("unroll") for (int k = 0; k < 2; ++k) dst[m][k] = *(const PG8_LAS bf16x8*)(lds + PG8_SA(b, h) + aoff + m * 2048 + k * 1024); } while (0)
; #define PG8_LDB(dst, b, h) do { _Pragma("unroll") for (int n = 0; n < 2; ++n) _Pragma("unroll") for (int k = 0; k < 2; ++k) dst[n][k] = *(const PG8_LAS bf16x8*)(lds + PG8_SB(b, h) + boff + n * 2048 + k * 1024); } while (0)
; #define PG8_MMA(ai, bj, At, Bt) do { __builtin_amdgcn_s_setprio(1); _Pragma("unroll") for (int m = 0; m < 4; ++m) _Pragma("unroll") for (int n = 0; n < 2; ++n) _Pragma("unroll") for (int k = 0; k < 2; ++k) \
;         acc[ai][bj][m][n] = __builtin_amdgcn_mfma_f32_16x16x32_bf16(Bt[n][k], At[m][k], acc[ai][bj][m][n], 0, 0, 0); __builtin_amdgcn_s_setprio(0); } while (0)
; #define PG8_WAIT_V(n) asm volatile("s_waitcnt vmcnt(" #n ")" ::: "memory")
; #define PG8_WAIT_L(n) asm volatile("s_waitcnt lgkmcnt(" #n ")" ::: "memory")
; #define PG8_BAR __builtin_amdgcn_s_barrier()
; #define PG8_SCHED __builtin_amdgcn_sched_barrier(0)
; template <class Epi, class Sched, bool ALIGN_EPI = false, bool SP2 = false>
; __device__ __forceinline__ void gemm_phase(PG8_LAS unsigned char* lds, const Gemm g, const Sched& S, const Epi& E) {
;     ...
;             PG8_LDB(B0, 0, 0); PG8_LDB(B1, 0, 1); PG8_SCHED; PG8_LDA(At, 0, 0); PG8_STAGE(PG8_SA(1, 1), a1 + hstepA, voffA);
;             PG8_WAIT_V(8); PG8_WAIT_L(0); PG8_BAR; PG8_MMA(0, 0, At, B0); PG8_MMA(0, 1, At, B1); PG8_BAR; PG8_SCHED;
;             PG8_LDA(At, 0, 1); PG8_STAGE(PG8_SB(0, 0), b2, voffB); PG8_STAGE(PG8_SB(0, 1), b2 + hstepB, voffB); PG8_STAGE(PG8_SA(0, 0), a2, voffA);
;             PG8_WAIT_V(8); PG8_WAIT_L(0); PG8_BAR; PG8_MMA(1, 0, At, B0); PG8_MMA(1, 1, At, B1); PG8_BAR; PG8_SCHED;
	v_mfma_f32_16x16x32_bf16 v[122:125], v[154:157], v[188:191], v[122:125]
	v_mfma_f32_16x16x32_bf16 v[126:129], v[162:165], v[188:191], v[126:129]
	v_mfma_f32_16x16x32_bf16 v[118:121], v[154:157], v[196:199], v[118:121]
	v_mfma_f32_16x16x32_bf16 v[106:109], v[162:165], v[196:199], v[106:109]
	v_mfma_f32_16x16x32_bf16 v[98:101], v[154:157], v[204:207], v[98:101]
	v_mfma_f32_16x16x32_bf16 v[90:93], v[162:165], v[204:207], v[90:93]
	v_mfma_f32_16x16x32_bf16 v[110:113], v[154:157], v[212:215], v[110:113]
	v_mfma_f32_16x16x32_bf16 v[82:85], v[162:165], v[212:215], v[82:85]
	v_mfma_f32_16x16x32_bf16 v[122:125], v[158:161], v[192:195], v[122:125]
	v_mfma_f32_16x16x32_bf16 v[126:129], v[166:169], v[192:195], v[126:129]
	v_mfma_f32_16x16x32_bf16 v[118:121], v[158:161], v[200:203], v[118:121]
	v_mfma_f32_16x16x32_bf16 v[106:109], v[166:169], v[200:203], v[106:109]
	v_mfma_f32_16x16x32_bf16 v[98:101], v[158:161], v[208:211], v[98:101]
	v_mfma_f32_16x16x32_bf16 v[90:93], v[166:169], v[208:211], v[90:93]
	v_mfma_f32_16x16x32_bf16 v[110:113], v[158:161], v[216:219], v[110:113]
	v_mfma_f32_16x16x32_bf16 v[82:85], v[166:169], v[216:219], v[82:85]
	v_mfma_f32_16x16x32_bf16 v[114:117], v[172:175], v[188:191], v[114:117]
	v_mfma_f32_16x16x32_bf16 v[102:105], v[180:183], v[188:191], v[102:105]
	v_mfma_f32_16x16x32_bf16 v[94:97], v[172:175], v[196:199], v[94:97]
	v_mfma_f32_16x16x32_bf16 v[86:89], v[180:183], v[196:199], v[86:89]
	v_mfma_f32_16x16x32_bf16 v[78:81], v[172:175], v[204:207], v[78:81]
	v_mfma_f32_16x16x32_bf16 v[70:73], v[180:183], v[204:207], v[70:73]
	v_mfma_f32_16x16x32_bf16 v[66:69], v[172:175], v[212:215], v[66:69]
	v_mfma_f32_16x16x32_bf16 v[74:77], v[180:183], v[212:215], v[74:77]
	v_mfma_f32_16x16x32_bf16 v[114:117], v[176:179], v[192:195], v[114:117]
	v_mfma_f32_16x16x32_bf16 v[102:105], v[184:187], v[192:195], v[102:105]
	v_mfma_f32_16x16x32_bf16 v[94:97], v[176:179], v[200:203], v[94:97]
	v_mfma_f32_16x16x32_bf16 v[86:89], v[184:187], v[200:203], v[86:89]
	v_mfma_f32_16x16x32_bf16 v[78:81], v[176:179], v[208:211], v[78:81]
	v_mfma_f32_16x16x32_bf16 v[70:73], v[184:187], v[208:211], v[70:73]
	v_mfma_f32_16x16x32_bf16 v[66:69], v[176:179], v[216:219], v[66:69]
	v_mfma_f32_16x16x32_bf16 v[74:77], v[184:187], v[216:219], v[74:77]
	s_barrier
	s_setprio 0
	s_add_i32 s66, s56, s44
	v_lshl_add_u64 v[220:221], s[40:41], 0, v[132:133]
	s_mov_b32 m0, s66
	ds_read_b128 v[188:191], v152 offset:16384
	ds_read_b128 v[192:195], v152 offset:17408
	ds_read_b128 v[196:199], v152 offset:18432
	ds_read_b128 v[200:203], v152 offset:19456
	ds_read_b128 v[204:207], v152 offset:20480
	ds_read_b128 v[208:211], v152 offset:21504
	ds_read_b128 v[212:215], v152 offset:22528
	ds_read_b128 v[216:219], v152 offset:23552
	s_add_i32 m0, s66, 0x2000
	s_add_u32 s66, s40, 0x100000
	v_lshl_add_u64 v[222:223], s[40:41], 0, v[136:137]
	s_addc_u32 s67, s41, 0
	s_add_i32 s68, s57, s44
	v_lshl_add_u64 v[224:225], s[66:67], 0, v[132:133]
	s_mov_b32 m0, s68
	s_nop 0
	v_lshl_add_u64 v[224:225], s[66:67], 0, v[136:137]
	s_add_i32 m0, s68, 0x2000
	s_nop 0
	v_lshl_add_u64 v[224:225], s[42:43], 0, v[130:131]
	s_mov_b32 m0, s45
	s_nop 0
	v_lshl_add_u64 v[224:225], s[42:43], 0, v[134:135]
	s_mov_b32 m0, s46
	s_nop 0
	s_waitcnt vmcnt(2)
	s_waitcnt lgkmcnt(0)
	s_setprio 1
	s_barrier
	v_mfma_f32_16x16x32_bf16 v[62:65], v[154:157], v[188:191], v[62:65]
	v_mfma_f32_16x16x32_bf16 v[58:61], v[162:165], v[188:191], v[58:61]
	v_mfma_f32_16x16x32_bf16 v[54:57], v[154:157], v[196:199], v[54:57]
	v_mfma_f32_16x16x32_bf16 v[46:49], v[162:165], v[196:199], v[46:49]
	v_mfma_f32_16x16x32_bf16 v[38:41], v[154:157], v[204:207], v[38:41]
	v_mfma_f32_16x16x32_bf16 v[30:33], v[162:165], v[204:207], v[30:33]
	v_mfma_f32_16x16x32_bf16 v[14:17], v[154:157], v[212:215], v[14:17]
	v_mfma_f32_16x16x32_bf16 v[10:13], v[162:165], v[212:215], v[10:13]
	v_mfma_f32_16x16x32_bf16 v[62:65], v[158:161], v[192:195], v[62:65]
	v_mfma_f32_16x16x32_bf16 v[58:61], v[166:169], v[192:195], v[58:61]
	v_mfma_f32_16x16x32_bf16 v[54:57], v[158:161], v[200:203], v[54:57]
	v_mfma_f32_16x16x32_bf16 v[46:49], v[166:169], v[200:203], v[46:49]
	v_mfma_f32_16x16x32_bf16 v[38:41], v[158:161], v[208:211], v[38:41]
	v_mfma_f32_16x16x32_bf16 v[30:33], v[166:169], v[208:211], v[30:33]
	v_mfma_f32_16x16x32_bf16 v[14:17], v[158:161], v[216:219], v[14:17]
	v_mfma_f32_16x16x32_bf16 v[10:13], v[166:169], v[216:219], v[10:13]
	v_mfma_f32_16x16x32_bf16 v[50:53], v[172:175], v[188:191], v[50:53]
	v_mfma_f32_16x16x32_bf16 v[42:45], v[180:183], v[188:191], v[42:45]
	v_mfma_f32_16x16x32_bf16 v[34:37], v[172:175], v[196:199], v[34:37]
	v_mfma_f32_16x16x32_bf16 v[26:29], v[180:183], v[196:199], v[26:29]
	v_mfma_f32_16x16x32_bf16 v[22:25], v[172:175], v[204:207], v[22:25]
	v_mfma_f32_16x16x32_bf16 v[18:21], v[180:183], v[204:207], v[18:21]
	v_mfma_f32_16x16x32_bf16 v[6:9], v[172:175], v[212:215], v[6:9]
	v_mfma_f32_16x16x32_bf16 v[2:5], v[180:183], v[212:215], v[2:5]
	v_mfma_f32_16x16x32_bf16 v[50:53], v[176:179], v[192:195], v[50:53]
	v_mfma_f32_16x16x32_bf16 v[42:45], v[184:187], v[192:195], v[42:45]
	v_mfma_f32_16x16x32_bf16 v[34:37], v[176:179], v[200:203], v[34:37]
	v_mfma_f32_16x16x32_bf16 v[26:29], v[184:187], v[200:203], v[26:29]
	v_mfma_f32_16x16x32_bf16 v[22:25], v[176:179], v[208:211], v[22:25]
	v_mfma_f32_16x16x32_bf16 v[18:21], v[184:187], v[208:211], v[18:21]
	v_mfma_f32_16x16x32_bf16 v[6:9], v[176:179], v[216:219], v[6:9]
	v_mfma_f32_16x16x32_bf16 v[2:5], v[184:187], v[216:219], v[2:5]
	s_barrier
; #define PG8_STAGE(bufoff, gbase, voff) do { _Pragma("unroll") for (int _i = 0; _i < 2; ++_i) \
;         __builtin_amdgcn_global_load_lds((const unsigned*)((const char*)(gbase) + (voff)[_i]), (PG8_LAS unsigned*)(lds + (bufoff) + ldsw + _i * 8192), 16, 0, 0); } while (0)
; #define PG8_LDA(dst, b, h) do { _Pragma("unroll") for (int m = 0; m < 4; ++m) _Pragma("unroll") for (int k = 0; k < 2; ++k) dst[m][k] = *(const PG8_LAS bf16x8*)(lds + PG8_SA(b, h) + aoff + m * 2048 + k * 1024); } while (0)
; #define PG8_LDB(dst, b, h) do { _Pragma("unroll") for (int n = 0; n < 2; ++n) _Pragma("unroll") for (int k = 0; k < 2; ++k) dst[n][k] = *(const PG8_LAS bf16x8*)(lds + PG8_SB(b, h) + boff + n * 2048 + k * 1024); } while (0)
; #define PG8_MMA(ai, bj, At, Bt) do { __builtin_amdgcn_s_setprio(1); _Pragma("unroll") for (int m = 0; m < 4; ++m) _Pragma("unroll") for (int n = 0; n < 2; ++n) _Pragma("unroll") for (int k = 0; k < 2; ++k) \
;         acc[ai][bj][m][n] = __builtin_amdgcn_mfma_f32_16x16x32_bf16(Bt[n][k], At[m][k], acc[ai][bj][m][n], 0, 0, 0); __builtin_amdgcn_s_setprio(0); } while (0)
; #define PG8_WAIT_V(n) asm volatile("s_waitcnt vmcnt(" #n ")" ::: "memory")
; #define PG8_WAIT_L(n) asm volatile("s_waitcnt lgkmcnt(" #n ")" ::: "memory")
; #define PG8_BAR __builtin_amdgcn_s_barrier()
; #define PG8_SCHED __builtin_amdgcn_sched_barrier(0)
; template <class Epi, class Sched, bool ALIGN_EPI = false, bool SP2 = false>
; __device__ __forceinline__ void gemm_phase(PG8_LAS unsigned char* lds, const Gemm g, const Sched& S, const Epi& E) {
;     ...
;             PG8_LDB(B0, 1, 0); PG8_LDB(B1, 1, 1); PG8_SCHED; PG8_LDA(At, 1, 0); PG8_STAGE(PG8_SA(0, 1), a2 + hstepA, voffA);
;             PG8_WAIT_V(8); PG8_WAIT_L(0); PG8_BAR; PG8_MMA(0, 0, At, B0); PG8_MMA(0, 1, At, B1); PG8_BAR; PG8_SCHED;
;             PG8_LDA(At, 1, 1); PG8_STAGE(PG8_SB(1, 0), b3, voffB); PG8_STAGE(PG8_SB(1, 1), b3 + hstepB, voffB); PG8_STAGE(PG8_SA(1, 0), a3, voffA);
;             PG8_WAIT_V(8); PG8_WAIT_L(0); PG8_BAR; PG8_MMA(1, 0, At, B0); PG8_MMA(1, 1, At, B1); PG8_BAR; PG8_SCHED;
	s_setprio 0
	s_add_i32 s66, 0, 0x18000
	v_add_u32_e32 v153, s66, v151
	s_add_i32 s67, 0, 0x1c000
	ds_read_b128 v[154:157], v153
	ds_read_b128 v[158:161], v153 offset:1024
	ds_read_b128 v[162:165], v153 offset:2048
	ds_read_b128 v[166:169], v153 offset:3072
	v_add_u32_e32 v153, s67, v151
	ds_read_b128 v[172:175], v153
	ds_read_b128 v[176:179], v153 offset:1024
	ds_read_b128 v[180:183], v153 offset:2048
	ds_read_b128 v[184:187], v153 offset:3072
	s_add_u32 s42, s42, 0x4000
	s_addc_u32 s43, s43, 0
	s_mov_b32 m0, s47
	v_lshl_add_u64 v[224:225], s[42:43], 0, v[130:131]
	ds_read_b128 v[188:191], v152 offset:32768
	ds_read_b128 v[192:195], v152 offset:33792
	ds_read_b128 v[196:199], v152 offset:34816
	ds_read_b128 v[200:203], v152 offset:35840
	ds_read_b128 v[204:207], v152 offset:36864
	ds_read_b128 v[208:211], v152 offset:37888
	ds_read_b128 v[212:215], v152 offset:38912
	ds_read_b128 v[216:219], v152 offset:39936
	v_lshl_add_u64 v[224:225], s[42:43], 0, v[134:135]
	s_mov_b32 m0, s48
	s_nop 0
	s_waitcnt vmcnt(0)
	s_waitcnt lgkmcnt(0)
	s_setprio 1
	s_barrier
	v_mfma_f32_16x16x32_bf16 v[122:125], v[154:157], v[188:191], v[122:125]
	v_mfma_f32_16x16x32_bf16 v[126:129], v[162:165], v[188:191], v[126:129]
	v_mfma_f32_16x16x32_bf16 v[118:121], v[154:157], v[196:199], v[118:121]
	v_mfma_f32_16x16x32_bf16 v[106:109], v[162:165], v[196:199], v[106:109]
	v_mfma_f32_16x16x32_bf16 v[98:101], v[154:157], v[204:207], v[98:101]
	v_mfma_f32_16x16x32_bf16 v[90:93], v[162:165], v[204:207], v[90:93]
	v_mfma_f32_16x16x32_bf16 v[110:113], v[154:157], v[212:215], v[110:113]
	v_mfma_f32_16x16x32_bf16 v[82:85], v[162:165], v[212:215], v[82:85]
	v_mfma_f32_16x16x32_bf16 v[122:125], v[158:161], v[192:195], v[122:125]
	v_mfma_f32_16x16x32_bf16 v[126:129], v[166:169], v[192:195], v[126:129]
	v_mfma_f32_16x16x32_bf16 v[118:121], v[158:161], v[200:203], v[118:121]
	v_mfma_f32_16x16x32_bf16 v[106:109], v[166:169], v[200:203], v[106:109]
	v_mfma_f32_16x16x32_bf16 v[98:101], v[158:161], v[208:211], v[98:101]
	v_mfma_f32_16x16x32_bf16 v[90:93], v[166:169], v[208:211], v[90:93]
	v_mfma_f32_16x16x32_bf16 v[110:113], v[158:161], v[216:219], v[110:113]
	v_mfma_f32_16x16x32_bf16 v[82:85], v[166:169], v[216:219], v[82:85]
	v_mfma_f32_16x16x32_bf16 v[114:117], v[172:175], v[188:191], v[114:117]
	v_mfma_f32_16x16x32_bf16 v[102:105], v[180:183], v[188:191], v[102:105]
	v_mfma_f32_16x16x32_bf16 v[94:97], v[172:175], v[196:199], v[94:97]
	v_mfma_f32_16x16x32_bf16 v[86:89], v[180:183], v[196:199], v[86:89]
	v_mfma_f32_16x16x32_bf16 v[78:81], v[172:175], v[204:207], v[78:81]
	v_mfma_f32_16x16x32_bf16 v[70:73], v[180:183], v[204:207], v[70:73]
	v_mfma_f32_16x16x32_bf16 v[66:69], v[172:175], v[212:215], v[66:69]
	v_mfma_f32_16x16x32_bf16 v[74:77], v[180:183], v[212:215], v[74:77]
	v_mfma_f32_16x16x32_bf16 v[114:117], v[176:179], v[192:195], v[114:117]
	v_mfma_f32_16x16x32_bf16 v[102:105], v[184:187], v[192:195], v[102:105]
	v_mfma_f32_16x16x32_bf16 v[94:97], v[176:179], v[200:203], v[94:97]
	v_mfma_f32_16x16x32_bf16 v[86:89], v[184:187], v[200:203], v[86:89]
	v_mfma_f32_16x16x32_bf16 v[78:81], v[176:179], v[208:211], v[78:81]
	v_mfma_f32_16x16x32_bf16 v[70:73], v[184:187], v[208:211], v[70:73]
	v_mfma_f32_16x16x32_bf16 v[66:69], v[176:179], v[216:219], v[66:69]
	v_mfma_f32_16x16x32_bf16 v[74:77], v[184:187], v[216:219], v[74:77]
	s_barrier
	s_setprio 0
	s_add_i32 s42, s66, s44
	v_lshl_add_u64 v[220:221], v[220:221], 0, s[16:17]
	s_mov_b32 m0, s42
	ds_read_b128 v[188:191], v152 offset:49152
	ds_read_b128 v[192:195], v152 offset:50176
	ds_read_b128 v[196:199], v152 offset:51200
	ds_read_b128 v[200:203], v152 offset:52224
	ds_read_b128 v[204:207], v152 offset:53248
	ds_read_b128 v[208:211], v152 offset:54272
	ds_read_b128 v[212:215], v152 offset:55296
	ds_read_b128 v[216:219], v152 offset:56320
	s_add_i32 m0, s42, 0x2000
	s_add_u32 s40, s40, 0x100080
	v_lshl_add_u64 v[220:221], v[222:223], 0, s[16:17]
	s_addc_u32 s41, s41, 0
	s_add_i32 s42, s67, s44
	v_lshl_add_u64 v[220:221], s[40:41], 0, v[132:133]
	s_mov_b32 m0, s42
	s_nop 0
	v_lshl_add_u64 v[220:221], s[40:41], 0, v[136:137]
	s_add_i32 m0, s42, 0x2000
	s_nop 0
	v_lshl_add_u64 v[220:221], s[38:39], 0, v[130:131]
	s_mov_b32 m0, s50
	s_nop 0
	v_lshl_add_u64 v[220:221], s[38:39], 0, v[134:135]
	s_mov_b32 m0, s51
	s_nop 0
	s_waitcnt vmcnt(0)
	s_waitcnt lgkmcnt(0)
	s_setprio 1
	s_barrier
	v_mfma_f32_16x16x32_bf16 v[62:65], v[154:157], v[188:191], v[62:65]
	v_mfma_f32_16x16x32_bf16 v[58:61], v[162:165], v[188:191], v[58:61]
	v_mfma_f32_16x16x32_bf16 v[54:57], v[154:157], v[196:199], v[54:57]
	v_mfma_f32_16x16x32_bf16 v[46:49], v[162:165], v[196:199], v[46:49]
	v_mfma_f32_16x16x32_bf16 v[38:41], v[154:157], v[204:207], v[38:41]
	v_mfma_f32_16x16x32_bf16 v[30:33], v[162:165], v[204:207], v[30:33]
	v_mfma_f32_16x16x32_bf16 v[14:17], v[154:157], v[212:215], v[14:17]
	v_mfma_f32_16x16x32_bf16 v[10:13], v[162:165], v[212:215], v[10:13]
	v_mfma_f32_16x16x32_bf16 v[62:65], v[158:161], v[192:195], v[62:65]
	v_mfma_f32_16x16x32_bf16 v[58:61], v[166:169], v[192:195], v[58:61]
	v_mfma_f32_16x16x32_bf16 v[54:57], v[158:161], v[200:203], v[54:57]
	v_mfma_f32_16x16x32_bf16 v[46:49], v[166:169], v[200:203], v[46:49]
	v_mfma_f32_16x16x32_bf16 v[38:41], v[158:161], v[208:211], v[38:41]
	v_mfma_f32_16x16x32_bf16 v[30:33], v[166:169], v[208:211], v[30:33]
	v_mfma_f32_16x16x32_bf16 v[14:17], v[158:161], v[216:219], v[14:17]
	v_mfma_f32_16x16x32_bf16 v[10:13], v[166:169], v[216:219], v[10:13]
	v_mfma_f32_16x16x32_bf16 v[50:53], v[172:175], v[188:191], v[50:53]
	v_mfma_f32_16x16x32_bf16 v[42:45], v[180:183], v[188:191], v[42:45]
	v_mfma_f32_16x16x32_bf16 v[34:37], v[172:175], v[196:199], v[34:37]
	v_mfma_f32_16x16x32_bf16 v[26:29], v[180:183], v[196:199], v[26:29]
	v_mfma_f32_16x16x32_bf16 v[22:25], v[172:175], v[204:207], v[22:25]
	v_mfma_f32_16x16x32_bf16 v[18:21], v[180:183], v[204:207], v[18:21]
	v_mfma_f32_16x16x32_bf16 v[6:9], v[172:175], v[212:215], v[6:9]
	v_mfma_f32_16x16x32_bf16 v[2:5], v[180:183], v[212:215], v[2:5]
	v_mfma_f32_16x16x32_bf16 v[50:53], v[176:179], v[192:195], v[50:53]
	v_mfma_f32_16x16x32_bf16 v[42:45], v[184:187], v[192:195], v[42:45]
	v_mfma_f32_16x16x32_bf16 v[34:37], v[176:179], v[200:203], v[34:37]
	v_mfma_f32_16x16x32_bf16 v[26:29], v[184:187], v[200:203], v[26:29]
	v_mfma_f32_16x16x32_bf16 v[22:25], v[176:179], v[208:211], v[22:25]
	v_mfma_f32_16x16x32_bf16 v[18:21], v[184:187], v[208:211], v[18:21]
	v_mfma_f32_16x16x32_bf16 v[6:9], v[176:179], v[216:219], v[6:9]
	v_mfma_f32_16x16x32_bf16 v[2:5], v[184:187], v[216:219], v[2:5]
	s_barrier
	s_setprio 0
	s_add_i32 s65, s65, 2
	s_add_u32 s63, s63, 0x100
	s_addc_u32 s64, s64, 0
	s_add_u32 s36, s36, 0x10000
	s_addc_u32 s37, s37, 0
	v_lshl_add_u64 v[148:149], v[148:149], 0, s[18:19]
	s_cmp_gt_u32 s65, 61
	v_lshl_add_u64 v[146:147], v[146:147], 0, s[18:19]
; template <class Epi, class Sched, bool ALIGN_EPI = false, bool SP2 = false>
; __device__ __forceinline__ void gemm_phase(PG8_LAS unsigned char* lds, const Gemm g, const Sched& S, const Epi& E) {
;     ...
;         bool keep_ = false;
;         if constexpr (!Epi::AFTER_DRAIN) { if constexpr (Epi::CARRY) keep_ = E.carry(acc, cur, wr, wc, fr, fq); else E(acc, cur, wr, wc, fr, fq); S.done(cur); }
;         if (!has_next) break;
;         if (!keep_) {
; #pragma unroll
;         for (int a = 0; a < 2; ++a)
; #pragma unroll
;             for (int b = 0; b < 2; ++b)
; #pragma unroll
;                 for (int m = 0; m < 4; ++m)
; #pragma unroll
;                     for (int n = 0; n < 2; ++n) acc[a][b][m][n] = (f32x4){0.f, 0.f, 0.f, 0.f};
;         }
;         cur = nxt; cA = nA; cB = nB; ++ui;
.Lpeel_p8_done:
	s_andn2_b64 vcc, exec, s[4:5]
	s_cbranch_vccnz .LBB0_1331
	v_mov_b32_e32 v2, 0
	s_mov_b32 s8, s22
	s_mov_b32 s6, s24
	s_mov_b64 s[10:11], s[30:31]
	s_mov_b64 s[14:15], s[28:29]
	s_mov_b32 s49, s58
	v_mov_b32_e32 v3, v2
	v_mov_b32_e32 v4, v2
	v_mov_b32_e32 v5, v2
	v_mov_b32_e32 v6, v2
	v_mov_b32_e32 v7, v2
	v_mov_b32_e32 v8, v2
	v_mov_b32_e32 v9, v2
	v_mov_b32_e32 v18, v2
	v_mov_b32_e32 v19, v2
	v_mov_b32_e32 v20, v2
	v_mov_b32_e32 v21, v2
	v_mov_b32_e32 v22, v2
	v_mov_b32_e32 v23, v2
	v_mov_b32_e32 v24, v2
	v_mov_b32_e32 v25, v2
	v_mov_b32_e32 v26, v2
	v_mov_b32_e32 v27, v2
	v_mov_b32_e32 v28, v2
	v_mov_b32_e32 v29, v2
	v_mov_b32_e32 v34, v2
	v_mov_b32_e32 v35, v2
	v_mov_b32_e32 v36, v2
	v_mov_b32_e32 v37, v2
	v_mov_b32_e32 v42, v2
	v_mov_b32_e32 v43, v2
	v_mov_b32_e32 v44, v2
	v_mov_b32_e32 v45, v2
	v_mov_b32_e32 v50, v2
	v_mov_b32_e32 v51, v2
	v_mov_b32_e32 v52, v2
	v_mov_b32_e32 v53, v2
	v_mov_b32_e32 v10, v2
	v_mov_b32_e32 v11, v2
	v_mov_b32_e32 v12, v2
	v_mov_b32_e32 v13, v2
	v_mov_b32_e32 v14, v2
	v_mov_b32_e32 v15, v2
	v_mov_b32_e32 v16, v2
	v_mov_b32_e32 v17, v2
	v_mov_b32_e32 v30, v2
	v_mov_b32_e32 v31, v2
	v_mov_b32_e32 v32, v2
	v_mov_b32_e32 v33, v2
	v_mov_b32_e32 v38, v2
	v_mov_b32_e32 v39, v2
	v_mov_b32_e32 v40, v2
	v_mov_b32_e32 v41, v2
	v_mov_b32_e32 v46, v2
	v_mov_b32_e32 v47, v2
	v_mov_b32_e32 v48, v2
	v_mov_b32_e32 v49, v2
	v_mov_b32_e32 v54, v2
	v_mov_b32_e32 v55, v2
	v_mov_b32_e32 v56, v2
	v_mov_b32_e32 v57, v2
	v_mov_b32_e32 v58, v2
	v_mov_b32_e32 v59, v2
	v_mov_b32_e32 v60, v2
	v_mov_b32_e32 v61, v2
	v_mov_b32_e32 v62, v2
	v_mov_b32_e32 v63, v2
	v_mov_b32_e32 v64, v2
	v_mov_b32_e32 v65, v2
	v_mov_b32_e32 v74, v2
	v_mov_b32_e32 v75, v2
	v_mov_b32_e32 v76, v2
	v_mov_b32_e32 v77, v2
	v_mov_b32_e32 v66, v2
	v_mov_b32_e32 v67, v2
	v_mov_b32_e32 v68, v2
	v_mov_b32_e32 v69, v2
	v_mov_b32_e32 v70, v2
	v_mov_b32_e32 v71, v2
	v_mov_b32_e32 v72, v2
	v_mov_b32_e32 v73, v2
	v_mov_b32_e32 v78, v2
	v_mov_b32_e32 v79, v2
	v_mov_b32_e32 v80, v2
	v_mov_b32_e32 v81, v2
	v_mov_b32_e32 v86, v2
	v_mov_b32_e32 v87, v2
	v_mov_b32_e32 v88, v2
	v_mov_b32_e32 v89, v2
	v_mov_b32_e32 v94, v2
	v_mov_b32_e32 v95, v2
	v_mov_b32_e32 v96, v2
	v_mov_b32_e32 v97, v2
	v_mov_b32_e32 v102, v2
	v_mov_b32_e32 v103, v2
	v_mov_b32_e32 v104, v2
	v_mov_b32_e32 v105, v2
	v_mov_b32_e32 v114, v2
	v_mov_b32_e32 v115, v2
	v_mov_b32_e32 v116, v2
	v_mov_b32_e32 v117, v2
	v_mov_b32_e32 v82, v2
	v_mov_b32_e32 v83, v2
	v_mov_b32_e32 v84, v2
	v_mov_b32_e32 v85, v2
	v_mov_b32_e32 v110, v2
	v_mov_b32_e32 v111, v2
	v_mov_b32_e32 v112, v2
	v_mov_b32_e32 v113, v2
	v_mov_b32_e32 v90, v2
	v_mov_b32_e32 v91, v2
	v_mov_b32_e32 v92, v2
	v_mov_b32_e32 v93, v2
	v_mov_b32_e32 v98, v2
	v_mov_b32_e32 v99, v2
	v_mov_b32_e32 v100, v2
	v_mov_b32_e32 v101, v2
	v_mov_b32_e32 v106, v2
	v_mov_b32_e32 v107, v2
	v_mov_b32_e32 v108, v2
	v_mov_b32_e32 v109, v2
	v_mov_b32_e32 v118, v2
	v_mov_b32_e32 v119, v2
	v_mov_b32_e32 v120, v2
	v_mov_b32_e32 v121, v2
	v_mov_b32_e32 v126, v2
	v_mov_b32_e32 v127, v2
	v_mov_b32_e32 v128, v2
	v_mov_b32_e32 v129, v2
	v_mov_b32_e32 v122, v2
	v_mov_b32_e32 v123, v2
	v_mov_b32_e32 v124, v2
	v_mov_b32_e32 v125, v2
	s_branch .LBB0_1331
